# epilogue xold prefetch: dummy loads pull residual rows into cache before the dependent load chain
# baseline (speedup 1.0000x reference)
; __device__ __forceinline__ unsigned cvt_pk_bf16(float lo, float hi) { unsigned r; asm volatile("v_cvt_pk_bf16_f32 %0, %1, %2" : "=v"(r) : "v"(lo), "v"(hi)); return r; }
; __device__ __forceinline__ float bflo(unsigned w) { return __uint_as_float(w << 16); }
; __device__ __forceinline__ float bfhi(unsigned w) { return __uint_as_float(w & 0xffff0000u); }
; template <bool RD32>
; __device__ __forceinline__ void res_rows(const float* __restrict__ xold32, const bf16_t* __restrict__ xoldb, bf16_t* __restrict__ xb, float* __restrict__ ssq, const f32x4 (&acc)[2][2][4][2], int row0, int col0, int slot) {
;     f32x4 xo[2][2][2];
;     float ssv[8];
;     auto ld = [&](size_t o, f32x4& a, f32x4& b) { if (RD32) { a = *(const f32x4*)(xold32 + o); b = *(const f32x4*)(xold32 + o + 4); }
;         else { const u32x4 w = *(const u32x4*)(xoldb + o); a = (f32x4){bflo(w.x), bfhi(w.x), bflo(w.y), bfhi(w.y)}; b = (f32x4){bflo(w.z), bfhi(w.z), bflo(w.w), bfhi(w.w)}; } };
; #pragma unroll
;     for (int bj = 0; bj < 2; ++bj) ld((size_t)row0 * D + col0 + bj * HALF, xo[0][bj][0], xo[0][bj][1]);
; #pragma unroll
;     for (int idx = 0; idx < 8; ++idx) {
;         const int ai = idx >> 2, m = idx & 3; const int r = row0 + ai * HALF + m * 16; const size_t off = (size_t)r * D + col0;
;         if (idx < 7) { const int ai2 = (idx + 1) >> 2, m2 = (idx + 1) & 3; const size_t off2 = (size_t)(row0 + ai2 * HALF + m2 * 16) * D + col0;
; #pragma unroll
;             for (int bj = 0; bj < 2; ++bj) ld(off2 + bj * HALF, xo[(idx + 1) & 1][bj][0], xo[(idx + 1) & 1][bj][1]); }
;         float ss = 0.f;
; #pragma unroll
;         for (int bj = 0; bj < 2; ++bj) { const f32x4 x0 = xo[idx & 1][bj][0] + acc[ai][bj][m][0], x1 = xo[idx & 1][bj][1] + acc[ai][bj][m][1];
;             u32x4 w; w.x = cvt_pk_bf16(x0[0], x0[1]); w.y = cvt_pk_bf16(x0[2], x0[3]); w.z = cvt_pk_bf16(x1[0], x1[1]); w.w = cvt_pk_bf16(x1[2], x1[3]);
;             *(u32x4*)(xb + off + bj * HALF) = w;
;             ss += ((x0[0] * x0[0] + x0[1] * x0[1]) + (x0[2] * x0[2] + x0[3] * x0[3])) + ((x1[0] * x1[0] + x1[1] * x1[1]) + (x1[2] * x1[2] + x1[3] * x1[3])); }
;         ss += __shfl_xor(ss, 16); ss += __shfl_xor(ss, 32);
;         ssv[idx] = ss;
.LBB0_421:
	v_lshl_add_u32 v166, s5, 8, v217
	v_lshl_or_b32 v132, s4, 8, v219
	v_lshl_or_b32 v222, s4, 2, v220
	v_ashrrev_i32_e32 v167, 31, v166
	v_or_b32_e32 v223, s95, v222
	v_ashrrev_i32_e32 v133, 31, v132
	s_andn2_b64 vcc, exec, s[48:49]
	v_lshlrev_b64 v[174:175], 11, v[166:167]
	v_or_b32_e32 v172, 16, v166
	v_or_b32_e32 v170, 32, v166
	v_or_b32_e32 v168, 48, v166
	s_cbranch_vccnz .LBB0_436
	v_lshlrev_b32_e32 v249, 11, v166
	v_lshl_add_u32 v249, v132, 1, v249
	global_load_dword v255, v249, s[58:59]
	global_load_dword v255, v249, s[58:59] offset:256
	v_add_u32_e32 v250, 0x8000, v249
	global_load_dword v255, v250, s[58:59]
	global_load_dword v255, v250, s[58:59] offset:256
	v_add_u32_e32 v250, 0x10000, v249
	global_load_dword v255, v250, s[58:59]
	global_load_dword v255, v250, s[58:59] offset:256
	v_add_u32_e32 v250, 0x18000, v249
	global_load_dword v255, v250, s[58:59]
	global_load_dword v255, v250, s[58:59] offset:256
	v_add_u32_e32 v250, 0x40000, v249
	global_load_dword v255, v250, s[58:59]
	global_load_dword v255, v250, s[58:59] offset:256
	v_add_u32_e32 v250, 0x48000, v249
	global_load_dword v255, v250, s[58:59]
	global_load_dword v255, v250, s[58:59] offset:256
	v_add_u32_e32 v250, 0x50000, v249
	global_load_dword v255, v250, s[58:59]
	global_load_dword v255, v250, s[58:59] offset:256
	v_add_u32_e32 v250, 0x58000, v249
	global_load_dword v255, v250, s[58:59]
	global_load_dword v255, v250, s[58:59] offset:256
	v_lshl_add_u64 v[128:129], s[58:59], 0, v[174:175]
	v_lshlrev_b64 v[134:135], 1, v[132:133]
	v_lshl_add_u64 v[136:137], v[128:129], 0, v[134:135]
	global_load_dwordx4 v[128:131], v[136:137], off
	v_ashrrev_i32_e32 v173, 31, v172
	v_ashrrev_i32_e32 v171, 31, v170
	s_mov_b64 s[4:5], 0x40000
	s_waitcnt vmcnt(0)
	v_lshlrev_b32_e32 v138, 16, v128
	v_and_b32_e32 v139, 0xffff0000, v128
	v_lshlrev_b32_e32 v140, 16, v129
	v_and_b32_e32 v141, 0xffff0000, v129
	v_lshlrev_b32_e32 v142, 16, v130
	v_and_b32_e32 v143, 0xffff0000, v130
	v_lshlrev_b32_e32 v176, 16, v131
	v_and_b32_e32 v177, 0xffff0000, v131
	global_load_dwordx4 v[128:131], v[136:137], off offset:256
	v_pk_add_f32 v[140:141], v[126:127], v[140:141]
	v_pk_add_f32 v[138:139], v[124:125], v[138:139]
	v_pk_add_f32 v[176:177], v[122:123], v[176:177]
	v_pk_add_f32 v[142:143], v[120:121], v[142:143]
	s_waitcnt vmcnt(0)
	v_lshlrev_b32_e32 v178, 16, v128
	v_and_b32_e32 v179, 0xffff0000, v128
	v_lshlrev_b32_e32 v180, 16, v129
	v_and_b32_e32 v181, 0xffff0000, v129
	v_lshlrev_b32_e32 v182, 16, v130
	v_and_b32_e32 v183, 0xffff0000, v130
	v_lshlrev_b32_e32 v202, 16, v131
	v_and_b32_e32 v203, 0xffff0000, v131
	v_lshl_add_u64 v[130:131], s[58:59], 0, v[134:135]
	v_lshlrev_b64 v[128:129], 11, v[172:173]
	v_lshl_add_u64 v[184:185], v[130:131], 0, v[128:129]
	global_load_dwordx4 v[134:137], v[184:185], off
	v_lshl_add_u64 v[128:129], v[130:131], 0, v[174:175]
	s_waitcnt vmcnt(0)
	v_lshlrev_b32_e32 v186, 16, v134
	v_and_b32_e32 v187, 0xffff0000, v134
	v_lshlrev_b32_e32 v190, 16, v135
	v_and_b32_e32 v191, 0xffff0000, v135
	v_lshlrev_b32_e32 v188, 16, v136
	v_and_b32_e32 v189, 0xffff0000, v136
	v_lshlrev_b32_e32 v192, 16, v137
	v_and_b32_e32 v193, 0xffff0000, v137
	global_load_dwordx4 v[134:137], v[184:185], off offset:256
	v_pk_add_f32 v[190:191], v[110:111], v[190:191]
	v_pk_add_f32 v[192:193], v[106:107], v[192:193]
	s_waitcnt vmcnt(0)
	v_lshlrev_b32_e32 v194, 16, v134
	v_and_b32_e32 v195, 0xffff0000, v134
	v_lshlrev_b32_e32 v198, 16, v135
	v_and_b32_e32 v199, 0xffff0000, v135
	v_cvt_pk_bf16_f32 v134, v138, v139
	v_cvt_pk_bf16_f32 v135, v140, v141
	v_lshlrev_b32_e32 v196, 16, v136
	v_and_b32_e32 v197, 0xffff0000, v136
	v_lshlrev_b32_e32 v200, 16, v137
	v_and_b32_e32 v201, 0xffff0000, v137
	v_cvt_pk_bf16_f32 v136, v142, v143
	v_cvt_pk_bf16_f32 v137, v176, v177
	global_store_dwordx4 v[128:129], v[134:137], off
	v_pk_add_f32 v[196:197], v[96:97], v[196:197]
	s_nop 0
	v_mul_f32_e32 v134, v139, v139
	v_mul_f32_e32 v135, v141, v141
	v_fmac_f32_e32 v134, v138, v138
	v_fmac_f32_e32 v135, v140, v140
	v_add_f32_e32 v134, v134, v135
	v_mul_f32_e32 v135, v143, v143
	v_mul_f32_e32 v136, v177, v177
	v_fmac_f32_e32 v135, v142, v142
	v_fmac_f32_e32 v136, v176, v176
	v_add_f32_e32 v135, v135, v136
	v_add_f32_e32 v152, v134, v135
	v_pk_add_f32 v[138:139], v[118:119], v[180:181]
	v_pk_add_f32 v[140:141], v[116:117], v[178:179]
	v_pk_add_f32 v[142:143], v[114:115], v[202:203]
	v_cvt_pk_bf16_f32 v134, v140, v141
	v_cvt_pk_bf16_f32 v135, v138, v139
	v_pk_add_f32 v[176:177], v[112:113], v[182:183]
	s_nop 0
	v_cvt_pk_bf16_f32 v136, v176, v177
	v_cvt_pk_bf16_f32 v137, v142, v143
	global_store_dwordx4 v[128:129], v[134:137], off offset:256
	s_nop 1
	v_mul_f32_e32 v134, v141, v141
	v_mul_f32_e32 v135, v139, v139
	v_fmac_f32_e32 v134, v140, v140
	v_fmac_f32_e32 v135, v138, v138
	v_add_f32_e32 v134, v134, v135
	v_mul_f32_e32 v135, v177, v177
	v_mul_f32_e32 v136, v143, v143
	v_fmac_f32_e32 v135, v176, v176
	v_fmac_f32_e32 v136, v142, v142
	v_add_f32_e32 v135, v135, v136
	v_and_b32_e32 v136, 64, v209
	v_add_f32_e32 v134, v134, v135
	v_xor_b32_e32 v135, 16, v209
	v_add_u32_e32 v136, 64, v136
	v_cmp_lt_i32_e32 vcc, v135, v136
	v_add_f32_e32 v134, v152, v134
	s_nop 0
	v_cndmask_b32_e32 v135, v209, v135, vcc
	v_lshlrev_b32_e32 v152, 2, v135
	ds_bpermute_b32 v135, v152, v134
	s_waitcnt lgkmcnt(0)
	v_add_f32_e32 v173, v134, v135
	v_xor_b32_e32 v134, 32, v209
	v_cmp_lt_i32_e32 vcc, v134, v136
	s_nop 1
	v_cndmask_b32_e32 v134, v209, v134, vcc
	v_lshlrev_b32_e32 v225, 2, v134
	v_lshlrev_b64 v[134:135], 11, v[170:171]
	v_lshl_add_u64 v[134:135], v[130:131], 0, v[134:135]
	global_load_dwordx4 v[136:139], v[134:135], off
	global_load_dwordx4 v[202:205], v[134:135], off offset:256
	v_mul_f32_e32 v171, v191, v191
	v_fmac_f32_e32 v171, v190, v190
	ds_bpermute_b32 v224, v225, v173
	s_waitcnt vmcnt(1)
; __device__ __forceinline__ unsigned cvt_pk_bf16(float lo, float hi) { unsigned r; asm volatile("v_cvt_pk_bf16_f32 %0, %1, %2" : "=v"(r) : "v"(lo), "v"(hi)); return r; }
; template <bool RD32>
; __device__ __forceinline__ void res_rows(const float* __restrict__ xold32, const bf16_t* __restrict__ xoldb, bf16_t* __restrict__ xb, float* __restrict__ ssq, const f32x4 (&acc)[2][2][4][2], int row0, int col0, int slot) {
;     ...
;     for (int idx = 0; idx < 8; ++idx) {
;         const int ai = idx >> 2, m = idx & 3; const int r = row0 + ai * HALF + m * 16; const size_t off = (size_t)r * D + col0;
;         if (idx < 7) { const int ai2 = (idx + 1) >> 2, m2 = (idx + 1) & 3; const size_t off2 = (size_t)(row0 + ai2 * HALF + m2 * 16) * D + col0;
; #pragma unroll
;             for (int bj = 0; bj < 2; ++bj) ld(off2 + bj * HALF, xo[(idx + 1) & 1][bj][0], xo[(idx + 1) & 1][bj][1]); }
;         float ss = 0.f;
; #pragma unroll
;         for (int bj = 0; bj < 2; ++bj) { const f32x4 x0 = xo[idx & 1][bj][0] + acc[ai][bj][m][0], x1 = xo[idx & 1][bj][1] + acc[ai][bj][m][1];
;             u32x4 w; w.x = cvt_pk_bf16(x0[0], x0[1]); w.y = cvt_pk_bf16(x0[2], x0[3]); w.z = cvt_pk_bf16(x1[0], x1[1]); w.w = cvt_pk_bf16(x1[2], x1[3]);
;             *(u32x4*)(xb + off + bj * HALF) = w;
;             ss += ((x0[0] * x0[0] + x0[1] * x0[1]) + (x0[2] * x0[2] + x0[3] * x0[3])) + ((x1[0] * x1[0] + x1[1] * x1[1]) + (x1[2] * x1[2] + x1[3] * x1[3])); }
;         ss += __shfl_xor(ss, 16); ss += __shfl_xor(ss, 32);
	v_lshlrev_b32_e32 v176, 16, v138
	v_and_b32_e32 v177, 0xffff0000, v138
	v_lshlrev_b32_e32 v180, 16, v139
	v_and_b32_e32 v181, 0xffff0000, v139
	s_waitcnt vmcnt(0)
	v_lshlrev_b32_e32 v138, 16, v202
	v_and_b32_e32 v139, 0xffff0000, v202
	v_lshlrev_b32_e32 v142, 16, v203
	v_and_b32_e32 v143, 0xffff0000, v203
	v_pk_add_f32 v[202:203], v[108:109], v[186:187]
	v_lshlrev_b32_e32 v178, 16, v136
	v_mul_f32_e32 v169, v203, v203
	v_and_b32_e32 v179, 0xffff0000, v136
	v_lshlrev_b32_e32 v182, 16, v137
	v_and_b32_e32 v183, 0xffff0000, v137
	v_lshlrev_b32_e32 v136, 16, v204
	v_and_b32_e32 v137, 0xffff0000, v204
	v_lshlrev_b32_e32 v140, 16, v205
	v_and_b32_e32 v141, 0xffff0000, v205
	v_pk_add_f32 v[204:205], v[104:105], v[188:189]
	v_cvt_pk_bf16_f32 v186, v202, v203
	v_fmac_f32_e32 v169, v202, v202
	v_cvt_pk_bf16_f32 v187, v190, v191
	v_cvt_pk_bf16_f32 v188, v204, v205
	v_cvt_pk_bf16_f32 v189, v192, v193
	global_store_dwordx4 v[184:185], v[186:189], off
	v_add_f32_e32 v169, v169, v171
	v_mul_f32_e32 v171, v205, v205
	v_mul_f32_e32 v186, v193, v193
	v_fmac_f32_e32 v171, v204, v204
	v_fmac_f32_e32 v186, v192, v192
	v_add_f32_e32 v171, v171, v186
	v_pk_add_f32 v[190:191], v[102:103], v[198:199]
	v_pk_add_f32 v[192:193], v[100:101], v[194:195]
	v_add_f32_e32 v169, v169, v171
	v_pk_add_f32 v[194:195], v[98:99], v[200:201]
	v_cvt_pk_bf16_f32 v186, v192, v193
	v_cvt_pk_bf16_f32 v187, v190, v191
	v_cvt_pk_bf16_f32 v188, v196, v197
	v_mul_f32_e32 v171, v193, v193
	v_cvt_pk_bf16_f32 v189, v194, v195
	global_store_dwordx4 v[184:185], v[186:189], off offset:256
	v_mul_f32_e32 v184, v191, v191
	v_fmac_f32_e32 v171, v192, v192
	v_fmac_f32_e32 v184, v190, v190
	v_add_f32_e32 v171, v171, v184
	v_mul_f32_e32 v184, v197, v197
	v_mul_f32_e32 v185, v195, v195
	v_fmac_f32_e32 v184, v196, v196
	v_fmac_f32_e32 v185, v194, v194
	v_add_f32_e32 v184, v184, v185
	v_add_f32_e32 v171, v171, v184
	v_add_f32_e32 v169, v169, v171
	ds_bpermute_b32 v171, v152, v169
	v_pk_add_f32 v[182:183], v[94:95], v[182:183]
	v_pk_add_f32 v[194:195], v[92:93], v[178:179]
	v_pk_add_f32 v[180:181], v[90:91], v[180:181]
	v_pk_add_f32 v[142:143], v[86:87], v[142:143]
	s_waitcnt lgkmcnt(0)
	v_add_f32_e32 v171, v169, v171
	v_ashrrev_i32_e32 v169, 31, v168
	v_lshlrev_b64 v[184:185], 11, v[168:169]
	v_lshl_add_u64 v[130:131], v[130:131], 0, v[184:185]
	global_load_dwordx4 v[184:187], v[130:131], off
	global_load_dwordx4 v[202:205], v[130:131], off offset:256
	v_mul_f32_e32 v169, v195, v195
	v_fmac_f32_e32 v169, v194, v194
	v_pk_add_f32 v[140:141], v[82:83], v[140:141]
	ds_bpermute_b32 v226, v225, v171
	s_waitcnt vmcnt(1)
	v_lshlrev_b32_e32 v192, 16, v186
	v_and_b32_e32 v193, 0xffff0000, v186
	v_lshlrev_b32_e32 v198, 16, v187
	v_and_b32_e32 v199, 0xffff0000, v187
	s_waitcnt vmcnt(0)
	v_lshlrev_b32_e32 v186, 16, v202
	v_and_b32_e32 v187, 0xffff0000, v202
	v_lshlrev_b32_e32 v190, 16, v203
	v_and_b32_e32 v191, 0xffff0000, v203
	v_pk_add_f32 v[202:203], v[88:89], v[176:177]
	v_cvt_pk_bf16_f32 v176, v194, v195
	v_cvt_pk_bf16_f32 v177, v182, v183
	v_lshlrev_b32_e32 v196, 16, v184
	v_cvt_pk_bf16_f32 v178, v202, v203
	v_cvt_pk_bf16_f32 v179, v180, v181
	global_store_dwordx4 v[134:135], v[176:179], off
	v_and_b32_e32 v197, 0xffff0000, v184
	v_lshlrev_b32_e32 v200, 16, v185
	v_mul_f32_e32 v176, v183, v183
	v_fmac_f32_e32 v176, v182, v182
	v_add_f32_e32 v169, v169, v176
	v_mul_f32_e32 v176, v203, v203
	v_mul_f32_e32 v177, v181, v181
	v_fmac_f32_e32 v176, v202, v202
	v_fmac_f32_e32 v177, v180, v180
	v_add_f32_e32 v176, v176, v177
	v_add_f32_e32 v169, v169, v176
	v_pk_add_f32 v[176:177], v[84:85], v[138:139]
	v_pk_add_f32 v[178:179], v[80:81], v[136:137]
	v_cvt_pk_bf16_f32 v136, v176, v177
	v_cvt_pk_bf16_f32 v137, v142, v143
	v_and_b32_e32 v201, 0xffff0000, v185
	v_cvt_pk_bf16_f32 v138, v178, v179
	v_cvt_pk_bf16_f32 v139, v140, v141
	global_store_dwordx4 v[134:135], v[136:139], off offset:256
	v_mul_f32_e32 v134, v177, v177
	v_mul_f32_e32 v135, v143, v143
	v_fmac_f32_e32 v134, v176, v176
	v_fmac_f32_e32 v135, v142, v142
	v_add_f32_e32 v134, v134, v135
	v_mul_f32_e32 v135, v179, v179
	v_mul_f32_e32 v136, v141, v141
	v_fmac_f32_e32 v135, v178, v178
	v_fmac_f32_e32 v136, v140, v140
	v_add_f32_e32 v135, v135, v136
	v_add_f32_e32 v134, v134, v135
	v_add_f32_e32 v134, v169, v134
	ds_bpermute_b32 v135, v152, v134
	v_lshlrev_b32_e32 v184, 16, v204
	v_and_b32_e32 v185, 0xffff0000, v204
	v_lshlrev_b32_e32 v188, 16, v205
	v_and_b32_e32 v189, 0xffff0000, v205
	s_waitcnt lgkmcnt(0)
	v_add_f32_e32 v169, v134, v135
	v_lshl_add_u64 v[134:135], v[128:129], 0, s[4:5]
	s_mov_b32 s4, 0x40000
	v_add_co_u32_e32 v136, vcc, s4, v128
	global_load_dwordx4 v[202:205], v[134:135], off offset:256
	s_nop 0
	v_addc_co_u32_e32 v137, vcc, 0, v129, vcc
	global_load_dwordx4 v[138:141], v[136:137], off
	v_pk_add_f32 v[192:193], v[72:73], v[192:193]
	v_pk_add_f32 v[200:201], v[78:79], v[200:201]
	v_pk_add_f32 v[190:191], v[70:71], v[190:191]
	v_pk_add_f32 v[188:189], v[66:67], v[188:189]
	s_mov_b64 s[4:5], 0x48000
	ds_bpermute_b32 v227, v225, v169
	s_waitcnt vmcnt(1)
	v_lshlrev_b32_e32 v176, 16, v203
	v_and_b32_e32 v177, 0xffff0000, v203
	v_lshlrev_b32_e32 v142, 16, v205
	s_waitcnt vmcnt(0)
; __device__ __forceinline__ unsigned cvt_pk_bf16(float lo, float hi) { unsigned r; asm volatile("v_cvt_pk_bf16_f32 %0, %1, %2" : "=v"(r) : "v"(lo), "v"(hi)); return r; }
; template <bool RD32>
; __device__ __forceinline__ void res_rows(const float* __restrict__ xold32, const bf16_t* __restrict__ xoldb, bf16_t* __restrict__ xb, float* __restrict__ ssq, const f32x4 (&acc)[2][2][4][2], int row0, int col0, int slot) {
;     ...
;     for (int idx = 0; idx < 8; ++idx) {
;         const int ai = idx >> 2, m = idx & 3; const int r = row0 + ai * HALF + m * 16; const size_t off = (size_t)r * D + col0;
;         if (idx < 7) { const int ai2 = (idx + 1) >> 2, m2 = (idx + 1) & 3; const size_t off2 = (size_t)(row0 + ai2 * HALF + m2 * 16) * D + col0;
; #pragma unroll
;             for (int bj = 0; bj < 2; ++bj) ld(off2 + bj * HALF, xo[(idx + 1) & 1][bj][0], xo[(idx + 1) & 1][bj][1]); }
;         float ss = 0.f;
; #pragma unroll
;         for (int bj = 0; bj < 2; ++bj) { const f32x4 x0 = xo[idx & 1][bj][0] + acc[ai][bj][m][0], x1 = xo[idx & 1][bj][1] + acc[ai][bj][m][1];
;             u32x4 w; w.x = cvt_pk_bf16(x0[0], x0[1]); w.y = cvt_pk_bf16(x0[2], x0[3]); w.z = cvt_pk_bf16(x1[0], x1[1]); w.w = cvt_pk_bf16(x1[2], x1[3]);
;             *(u32x4*)(xb + off + bj * HALF) = w;
;             ss += ((x0[0] * x0[0] + x0[1] * x0[1]) + (x0[2] * x0[2] + x0[3] * x0[3])) + ((x1[0] * x1[0] + x1[1] * x1[1]) + (x1[2] * x1[2] + x1[3] * x1[3])); }
;         ss += __shfl_xor(ss, 16); ss += __shfl_xor(ss, 32);
	v_lshlrev_b32_e32 v180, 16, v138
	v_and_b32_e32 v181, 0xffff0000, v138
	v_lshlrev_b32_e32 v194, 16, v139
	v_and_b32_e32 v195, 0xffff0000, v139
	v_lshlrev_b32_e32 v178, 16, v140
	v_and_b32_e32 v179, 0xffff0000, v140
	v_lshlrev_b32_e32 v182, 16, v141
	v_and_b32_e32 v183, 0xffff0000, v141
	v_lshlrev_b32_e32 v140, 16, v202
	v_and_b32_e32 v141, 0xffff0000, v202
	v_lshlrev_b32_e32 v138, 16, v204
	v_and_b32_e32 v139, 0xffff0000, v204
	v_and_b32_e32 v143, 0xffff0000, v205
	v_pk_add_f32 v[202:203], v[76:77], v[196:197]
	v_pk_add_f32 v[204:205], v[74:75], v[198:199]
	v_cvt_pk_bf16_f32 v196, v202, v203
	v_cvt_pk_bf16_f32 v197, v200, v201
	v_cvt_pk_bf16_f32 v198, v192, v193
	v_mul_f32_e32 v193, v193, v193
	v_cvt_pk_bf16_f32 v199, v204, v205
	global_store_dwordx4 v[130:131], v[196:199], off
	v_fmac_f32_e32 v193, v192, v192
	v_mul_f32_e32 v192, v205, v205
	v_mul_f32_e32 v196, v203, v203
	v_mul_f32_e32 v197, v201, v201
	v_fmac_f32_e32 v196, v202, v202
	v_fmac_f32_e32 v197, v200, v200
	v_fmac_f32_e32 v192, v204, v204
	v_add_f32_e32 v196, v196, v197
	v_add_f32_e32 v192, v193, v192
	v_add_f32_e32 v198, v196, v192
	v_pk_add_f32 v[192:193], v[68:69], v[186:187]
	v_pk_add_f32 v[196:197], v[64:65], v[184:185]
	v_cvt_pk_bf16_f32 v184, v192, v193
	v_cvt_pk_bf16_f32 v185, v190, v191
	v_pk_add_f32 v[182:183], v[58:59], v[182:183]
	v_cvt_pk_bf16_f32 v186, v196, v197
	v_cvt_pk_bf16_f32 v187, v188, v189
	global_store_dwordx4 v[130:131], v[184:187], off offset:256
	v_mul_f32_e32 v130, v193, v193
	v_mul_f32_e32 v131, v191, v191
	v_fmac_f32_e32 v130, v192, v192
	v_fmac_f32_e32 v131, v190, v190
	v_add_f32_e32 v130, v130, v131
	v_mul_f32_e32 v131, v197, v197
	v_mul_f32_e32 v184, v189, v189
	v_fmac_f32_e32 v131, v196, v196
	v_fmac_f32_e32 v184, v188, v188
	v_add_f32_e32 v131, v131, v184
	v_add_f32_e32 v130, v130, v131
	v_add_f32_e32 v130, v198, v130
	ds_bpermute_b32 v131, v152, v130
	v_pk_add_f32 v[184:185], v[62:63], v[194:195]
	v_pk_add_f32 v[194:195], v[60:61], v[180:181]
	v_pk_add_f32 v[176:177], v[54:55], v[176:177]
	v_pk_add_f32 v[140:141], v[52:53], v[140:141]
	s_waitcnt lgkmcnt(0)
	v_add_f32_e32 v228, v130, v131
	v_lshl_add_u64 v[130:131], v[128:129], 0, s[4:5]
	s_mov_b32 s4, 0x48000
	v_add_co_u32_e32 v186, vcc, s4, v128
	global_load_dwordx4 v[230:233], v[130:131], off offset:256
	s_nop 0
	v_addc_co_u32_e32 v187, vcc, 0, v129, vcc
	global_load_dwordx4 v[188:191], v[186:187], off
	v_pk_add_f32 v[142:143], v[50:51], v[142:143]
	s_mov_b64 s[4:5], 0x50000
	ds_bpermute_b32 v229, v225, v228
	s_waitcnt vmcnt(1)
	v_lshlrev_b32_e32 v196, 16, v231
	v_and_b32_e32 v197, 0xffff0000, v231
	v_lshlrev_b32_e32 v192, 16, v233
	s_waitcnt vmcnt(0)
	v_lshlrev_b32_e32 v198, 16, v190
	v_and_b32_e32 v199, 0xffff0000, v190
	v_lshlrev_b32_e32 v202, 16, v191
	v_and_b32_e32 v203, 0xffff0000, v191
	v_lshlrev_b32_e32 v190, 16, v230
	v_and_b32_e32 v191, 0xffff0000, v230
	v_pk_add_f32 v[230:231], v[56:57], v[178:179]
	v_cvt_pk_bf16_f32 v178, v194, v195
	v_cvt_pk_bf16_f32 v179, v184, v185
	v_lshlrev_b32_e32 v200, 16, v188
	v_cvt_pk_bf16_f32 v180, v230, v231
	v_cvt_pk_bf16_f32 v181, v182, v183
	global_store_dwordx4 v[136:137], v[178:181], off
	v_mul_f32_e32 v136, v195, v195
	v_mul_f32_e32 v137, v185, v185
	v_fmac_f32_e32 v136, v194, v194
	v_fmac_f32_e32 v137, v184, v184
	v_add_f32_e32 v136, v136, v137
	v_mul_f32_e32 v137, v231, v231
	v_mul_f32_e32 v178, v183, v183
	v_fmac_f32_e32 v137, v230, v230
	v_fmac_f32_e32 v178, v182, v182
	v_add_f32_e32 v137, v137, v178
	v_add_f32_e32 v180, v136, v137
	v_pk_add_f32 v[178:179], v[48:49], v[138:139]
	v_cvt_pk_bf16_f32 v136, v140, v141
	v_cvt_pk_bf16_f32 v137, v176, v177
	v_and_b32_e32 v201, 0xffff0000, v188
	v_cvt_pk_bf16_f32 v138, v178, v179
	v_cvt_pk_bf16_f32 v139, v142, v143
	global_store_dwordx4 v[134:135], v[136:139], off offset:256
	v_mul_f32_e32 v134, v141, v141
	v_mul_f32_e32 v135, v177, v177
	v_fmac_f32_e32 v134, v140, v140
	v_fmac_f32_e32 v135, v176, v176
	v_add_f32_e32 v134, v134, v135
	v_mul_f32_e32 v135, v179, v179
	v_mul_f32_e32 v136, v143, v143
	v_fmac_f32_e32 v135, v178, v178
	v_fmac_f32_e32 v136, v142, v142
	v_add_f32_e32 v135, v135, v136
	v_add_f32_e32 v134, v134, v135
	v_add_f32_e32 v134, v180, v134
	ds_bpermute_b32 v135, v152, v134
	v_lshlrev_b32_e32 v204, 16, v189
	v_and_b32_e32 v205, 0xffff0000, v189
	v_lshlrev_b32_e32 v188, 16, v232
	v_and_b32_e32 v189, 0xffff0000, v232
	s_waitcnt lgkmcnt(0)
	v_add_f32_e32 v230, v134, v135
	v_lshl_add_u64 v[134:135], v[128:129], 0, s[4:5]
	s_mov_b32 s4, 0x50000
	v_add_co_u32_e32 v136, vcc, s4, v128
	v_and_b32_e32 v193, 0xffff0000, v233
	s_nop 0
	v_addc_co_u32_e32 v137, vcc, 0, v129, vcc
	global_load_dwordx4 v[176:179], v[136:137], off
	global_load_dwordx4 v[232:235], v[134:135], off offset:256
	v_pk_add_f32 v[194:195], v[46:47], v[204:205]
	v_pk_add_f32 v[204:205], v[44:45], v[200:201]
	v_pk_add_f32 v[202:203], v[42:43], v[202:203]
	v_pk_add_f32 v[190:191], v[36:37], v[190:191]
	v_pk_add_f32 v[192:193], v[34:35], v[192:193]
	s_mov_b64 s[4:5], 0x58000
	ds_bpermute_b32 v231, v225, v230
	s_waitcnt vmcnt(1)
	v_lshlrev_b32_e32 v140, 16, v176
	s_waitcnt vmcnt(0)
; __device__ __forceinline__ unsigned cvt_pk_bf16(float lo, float hi) { unsigned r; asm volatile("v_cvt_pk_bf16_f32 %0, %1, %2" : "=v"(r) : "v"(lo), "v"(hi)); return r; }
; template <bool RD32>
; __device__ __forceinline__ void res_rows(const float* __restrict__ xold32, const bf16_t* __restrict__ xoldb, bf16_t* __restrict__ xb, float* __restrict__ ssq, const f32x4 (&acc)[2][2][4][2], int row0, int col0, int slot) {
;     ...
;     for (int idx = 0; idx < 8; ++idx) {
;         const int ai = idx >> 2, m = idx & 3; const int r = row0 + ai * HALF + m * 16; const size_t off = (size_t)r * D + col0;
;         if (idx < 7) { const int ai2 = (idx + 1) >> 2, m2 = (idx + 1) & 3; const size_t off2 = (size_t)(row0 + ai2 * HALF + m2 * 16) * D + col0;
; #pragma unroll
;             for (int bj = 0; bj < 2; ++bj) ld(off2 + bj * HALF, xo[(idx + 1) & 1][bj][0], xo[(idx + 1) & 1][bj][1]); }
;         float ss = 0.f;
; #pragma unroll
;         for (int bj = 0; bj < 2; ++bj) { const f32x4 x0 = xo[idx & 1][bj][0] + acc[ai][bj][m][0], x1 = xo[idx & 1][bj][1] + acc[ai][bj][m][1];
;             u32x4 w; w.x = cvt_pk_bf16(x0[0], x0[1]); w.y = cvt_pk_bf16(x0[2], x0[3]); w.z = cvt_pk_bf16(x1[0], x1[1]); w.w = cvt_pk_bf16(x1[2], x1[3]);
;             *(u32x4*)(xb + off + bj * HALF) = w;
;             ss += ((x0[0] * x0[0] + x0[1] * x0[1]) + (x0[2] * x0[2] + x0[3] * x0[3])) + ((x1[0] * x1[0] + x1[1] * x1[1]) + (x1[2] * x1[2] + x1[3] * x1[3])); }
;         ss += __shfl_xor(ss, 16); ss += __shfl_xor(ss, 32);
;         ssv[idx] = ss;
;     }
;     const int fq = slot >> 6;
; #pragma unroll
;     for (int j = 0; j < 2; ++j) { const float v = fq == 0 ? ssv[j] : fq == 1 ? ssv[2 + j] : fq == 2 ? ssv[4 + j] : ssv[6 + j]; const int idx = 2 * fq + j;
;         ssq[(size_t)(row0 + (idx >> 2) * HALF + (idx & 3) * 16) * 16 + (slot & 15)] = v; }
	v_lshlrev_b32_e32 v180, 16, v232
	v_and_b32_e32 v181, 0xffff0000, v232
	v_lshlrev_b32_e32 v184, 16, v233
	v_and_b32_e32 v185, 0xffff0000, v233
	v_pk_add_f32 v[232:233], v[40:41], v[198:199]
	v_cvt_pk_bf16_f32 v198, v204, v205
	v_cvt_pk_bf16_f32 v199, v194, v195
	v_and_b32_e32 v141, 0xffff0000, v176
	v_cvt_pk_bf16_f32 v200, v232, v233
	v_cvt_pk_bf16_f32 v201, v202, v203
	global_store_dwordx4 v[186:187], v[198:201], off
	v_mul_f32_e32 v186, v205, v205
	v_mul_f32_e32 v187, v195, v195
	v_fmac_f32_e32 v186, v204, v204
	v_fmac_f32_e32 v187, v194, v194
	v_add_f32_e32 v186, v186, v187
	v_mul_f32_e32 v187, v233, v233
	v_mul_f32_e32 v194, v203, v203
	v_fmac_f32_e32 v187, v232, v232
	v_fmac_f32_e32 v194, v202, v202
	v_add_f32_e32 v187, v187, v194
	v_pk_add_f32 v[194:195], v[38:39], v[196:197]
	v_add_f32_e32 v198, v186, v187
	v_pk_add_f32 v[196:197], v[32:33], v[188:189]
	v_cvt_pk_bf16_f32 v186, v190, v191
	v_cvt_pk_bf16_f32 v187, v194, v195
	v_lshlrev_b32_e32 v176, 16, v177
	v_cvt_pk_bf16_f32 v188, v196, v197
	v_cvt_pk_bf16_f32 v189, v192, v193
	global_store_dwordx4 v[130:131], v[186:189], off offset:256
	v_mul_f32_e32 v130, v191, v191
	v_mul_f32_e32 v131, v195, v195
	v_fmac_f32_e32 v130, v190, v190
	v_fmac_f32_e32 v131, v194, v194
	v_add_f32_e32 v130, v130, v131
	v_mul_f32_e32 v131, v197, v197
	v_mul_f32_e32 v186, v193, v193
	v_fmac_f32_e32 v131, v196, v196
	v_fmac_f32_e32 v186, v192, v192
	v_add_f32_e32 v131, v131, v186
	v_add_f32_e32 v130, v130, v131
	v_add_f32_e32 v130, v198, v130
	ds_bpermute_b32 v131, v152, v130
	v_lshl_add_u64 v[186:187], v[128:129], 0, s[4:5]
	s_mov_b32 s4, 0x58000
	v_add_co_u32_e32 v188, vcc, s4, v128
	s_waitcnt lgkmcnt(0)
	v_add_f32_e32 v198, v130, v131
	v_addc_co_u32_e32 v189, vcc, 0, v129, vcc
	global_load_dwordx4 v[128:131], v[188:189], off
	v_and_b32_e32 v177, 0xffff0000, v177
	v_lshlrev_b32_e32 v138, 16, v178
	v_and_b32_e32 v139, 0xffff0000, v178
	v_lshlrev_b32_e32 v142, 16, v179
	v_and_b32_e32 v143, 0xffff0000, v179
	v_pk_add_f32 v[176:177], v[30:31], v[176:177]
	v_pk_add_f32 v[140:141], v[28:29], v[140:141]
	v_pk_add_f32 v[142:143], v[26:27], v[142:143]
	v_pk_add_f32 v[138:139], v[24:25], v[138:139]
	v_lshlrev_b32_e32 v178, 16, v234
	v_and_b32_e32 v179, 0xffff0000, v234
	v_lshlrev_b32_e32 v182, 16, v235
	v_and_b32_e32 v183, 0xffff0000, v235
	ds_bpermute_b32 v199, v225, v198
	v_cmp_lt_u32_e32 vcc, 63, v222
	s_waitcnt vmcnt(0)
	v_lshlrev_b32_e32 v192, 16, v128
	v_and_b32_e32 v193, 0xffff0000, v128
	v_lshlrev_b32_e32 v196, 16, v129
	v_and_b32_e32 v197, 0xffff0000, v129
	v_lshlrev_b32_e32 v190, 16, v130
	v_and_b32_e32 v191, 0xffff0000, v130
	v_lshlrev_b32_e32 v194, 16, v131
	v_and_b32_e32 v195, 0xffff0000, v131
	global_load_dwordx4 v[128:131], v[186:187], off offset:256
	s_waitcnt vmcnt(0)
	v_lshlrev_b32_e32 v200, 16, v128
	v_and_b32_e32 v201, 0xffff0000, v128
	v_lshlrev_b32_e32 v202, 16, v129
	v_and_b32_e32 v203, 0xffff0000, v129
	v_cvt_pk_bf16_f32 v128, v140, v141
	v_cvt_pk_bf16_f32 v129, v176, v177
	v_lshlrev_b32_e32 v204, 16, v130
	v_and_b32_e32 v205, 0xffff0000, v130
	v_lshlrev_b32_e32 v232, 16, v131
	v_and_b32_e32 v233, 0xffff0000, v131
	v_cvt_pk_bf16_f32 v130, v138, v139
	v_cvt_pk_bf16_f32 v131, v142, v143
	global_store_dwordx4 v[136:137], v[128:131], off
	v_pk_add_f32 v[136:137], v[22:23], v[184:185]
	s_nop 0
	v_mul_f32_e32 v128, v141, v141
	v_mul_f32_e32 v129, v177, v177
	v_fmac_f32_e32 v128, v140, v140
	v_fmac_f32_e32 v129, v176, v176
	v_add_f32_e32 v128, v128, v129
	v_mul_f32_e32 v129, v139, v139
	v_mul_f32_e32 v130, v143, v143
	v_fmac_f32_e32 v129, v138, v138
	v_fmac_f32_e32 v130, v142, v142
	v_add_f32_e32 v129, v129, v130
	v_add_f32_e32 v176, v128, v129
	v_pk_add_f32 v[138:139], v[20:21], v[180:181]
	v_pk_add_f32 v[140:141], v[18:19], v[182:183]
	v_cvt_pk_bf16_f32 v128, v138, v139
	v_cvt_pk_bf16_f32 v129, v136, v137
	v_pk_add_f32 v[142:143], v[16:17], v[178:179]
	s_nop 0
	v_cvt_pk_bf16_f32 v130, v142, v143
	v_cvt_pk_bf16_f32 v131, v140, v141
	global_store_dwordx4 v[134:135], v[128:131], off offset:256
	s_nop 1
	v_mul_f32_e32 v128, v139, v139
	v_mul_f32_e32 v129, v137, v137
	v_fmac_f32_e32 v128, v138, v138
	v_fmac_f32_e32 v129, v136, v136
	v_add_f32_e32 v128, v128, v129
	v_mul_f32_e32 v129, v143, v143
	v_mul_f32_e32 v130, v141, v141
	v_fmac_f32_e32 v129, v142, v142
	v_fmac_f32_e32 v130, v140, v140
	v_add_f32_e32 v129, v129, v130
	v_add_f32_e32 v128, v128, v129
	v_add_f32_e32 v128, v176, v128
	ds_bpermute_b32 v129, v152, v128
	v_pk_add_f32 v[130:131], v[14:15], v[196:197]
	v_pk_add_f32 v[140:141], v[12:13], v[192:193]
	v_pk_add_f32 v[142:143], v[10:11], v[194:195]
	v_cvt_pk_bf16_f32 v136, v140, v141
	s_waitcnt lgkmcnt(0)
	v_add_f32_e32 v129, v128, v129
	v_cvt_pk_bf16_f32 v137, v130, v131
	v_mul_f32_e32 v128, v141, v141
	v_mul_f32_e32 v131, v131, v131
	v_pk_add_f32 v[176:177], v[8:9], v[190:191]
	v_fmac_f32_e32 v128, v140, v140
	v_fmac_f32_e32 v131, v130, v130
	v_add_f32_e32 v128, v128, v131
	v_mul_f32_e32 v130, v177, v177
	v_mul_f32_e32 v131, v143, v143
	v_fmac_f32_e32 v130, v176, v176
	v_fmac_f32_e32 v131, v142, v142
	v_add_f32_e32 v130, v130, v131
	v_add_f32_e32 v128, v128, v130
	v_pk_add_f32 v[130:131], v[6:7], v[202:203]
	v_pk_add_f32 v[140:141], v[4:5], v[200:201]
	v_cvt_pk_bf16_f32 v138, v176, v177
	v_cvt_pk_bf16_f32 v139, v142, v143
	global_store_dwordx4 v[188:189], v[136:139], off
	v_mul_f32_e32 v134, v141, v141
	v_pk_add_f32 v[142:143], v[2:3], v[232:233]
	v_cvt_pk_bf16_f32 v136, v140, v141
	v_cvt_pk_bf16_f32 v137, v130, v131
	v_mul_f32_e32 v131, v131, v131
	v_pk_add_f32 v[176:177], v[0:1], v[204:205]
	v_fmac_f32_e32 v134, v140, v140
	v_fmac_f32_e32 v131, v130, v130
	v_add_f32_e32 v130, v134, v131
	v_mul_f32_e32 v131, v177, v177
	v_mul_f32_e32 v134, v143, v143
	v_fmac_f32_e32 v131, v176, v176
	v_fmac_f32_e32 v134, v142, v142
	v_add_f32_e32 v131, v131, v134
	v_add_f32_e32 v130, v130, v131
	v_add_f32_e32 v128, v128, v130
	ds_bpermute_b32 v130, v152, v128
	v_cvt_pk_bf16_f32 v138, v176, v177
	v_cvt_pk_bf16_f32 v139, v142, v143
	global_store_dwordx4 v[186:187], v[136:139], off offset:256
	ds_bpermute_b32 v135, v225, v129
	s_waitcnt lgkmcnt(1)
	v_add_f32_e32 v136, v128, v130
	ds_bpermute_b32 v137, v225, v136
	v_and_b32_e32 v130, 15, v223
	v_and_b32_e32 v128, 0xffffff80, v222
	v_lshlrev_b32_e32 v152, 2, v130
	v_add_u32_e32 v128, v166, v128
	v_lshl_add_u64 v[130:131], s[18:19], 0, v[152:153]
	s_and_saveexec_b64 s[4:5], vcc
	s_xor_b64 s[24:25], exec, s[4:5]
	s_cbranch_execz .LBB0_433
	v_ashrrev_i32_e32 v138, 6, v222
	v_cmp_lt_i32_e32 vcc, 1, v138
	s_mov_b64 s[36:37], 0
	s_and_saveexec_b64 s[4:5], vcc
	s_xor_b64 s[38:39], exec, s[4:5]
	s_cbranch_execnz .LBB0_454
	s_or_saveexec_b64 s[38:39], s[38:39]
	v_cmp_ne_u32_e32 vcc, 1, v138
	s_xor_b64 exec, exec, s[38:39]
	s_cbranch_execnz .LBB0_457

; __device__ __forceinline__ unsigned cvt_pk_bf16(float lo, float hi) { unsigned r; asm volatile("v_cvt_pk_bf16_f32 %0, %1, %2" : "=v"(r) : "v"(lo), "v"(hi)); return r; }
; __device__ __forceinline__ float bflo(unsigned w) { return __uint_as_float(w << 16); }
; __device__ __forceinline__ float bfhi(unsigned w) { return __uint_as_float(w & 0xffff0000u); }
; template <bool RD32>
; __device__ __forceinline__ void res_rows(const float* __restrict__ xold32, const bf16_t* __restrict__ xoldb, bf16_t* __restrict__ xb, float* __restrict__ ssq, const f32x4 (&acc)[2][2][4][2], int row0, int col0, int slot) {
;     f32x4 xo[2][2][2];
;     float ssv[8];
;     auto ld = [&](size_t o, f32x4& a, f32x4& b) { if (RD32) { a = *(const f32x4*)(xold32 + o); b = *(const f32x4*)(xold32 + o + 4); }
;         else { const u32x4 w = *(const u32x4*)(xoldb + o); a = (f32x4){bflo(w.x), bfhi(w.x), bflo(w.y), bfhi(w.y)}; b = (f32x4){bflo(w.z), bfhi(w.z), bflo(w.w), bfhi(w.w)}; } };
; #pragma unroll
;     for (int bj = 0; bj < 2; ++bj) ld((size_t)row0 * D + col0 + bj * HALF, xo[0][bj][0], xo[0][bj][1]);
; #pragma unroll
;     for (int idx = 0; idx < 8; ++idx) {
;         const int ai = idx >> 2, m = idx & 3; const int r = row0 + ai * HALF + m * 16; const size_t off = (size_t)r * D + col0;
;         if (idx < 7) { const int ai2 = (idx + 1) >> 2, m2 = (idx + 1) & 3; const size_t off2 = (size_t)(row0 + ai2 * HALF + m2 * 16) * D + col0;
; #pragma unroll
;             for (int bj = 0; bj < 2; ++bj) ld(off2 + bj * HALF, xo[(idx + 1) & 1][bj][0], xo[(idx + 1) & 1][bj][1]); }
;         float ss = 0.f;
; #pragma unroll
;         for (int bj = 0; bj < 2; ++bj) { const f32x4 x0 = xo[idx & 1][bj][0] + acc[ai][bj][m][0], x1 = xo[idx & 1][bj][1] + acc[ai][bj][m][1];
;             u32x4 w; w.x = cvt_pk_bf16(x0[0], x0[1]); w.y = cvt_pk_bf16(x0[2], x0[3]); w.z = cvt_pk_bf16(x1[0], x1[1]); w.w = cvt_pk_bf16(x1[2], x1[3]);
;             *(u32x4*)(xb + off + bj * HALF) = w;
;             ss += ((x0[0] * x0[0] + x0[1] * x0[1]) + (x0[2] * x0[2] + x0[3] * x0[3])) + ((x1[0] * x1[0] + x1[1] * x1[1]) + (x1[2] * x1[2] + x1[3] * x1[3])); }
;         ss += __shfl_xor(ss, 16); ss += __shfl_xor(ss, 32);
;         ssv[idx] = ss;
.LBB0_436:
.LBB0_437:
	v_readlane_b32 s4, v248, 0
	v_lshlrev_b64 v[128:129], 12, v[166:167]
	v_readlane_b32 s5, v248, 1
	v_lshlrev_b64 v[130:131], 2, v[132:133]
	v_ashrrev_i32_e32 v173, 31, v172
	v_lshl_add_u64 v[128:129], s[4:5], 0, v[128:129]
	v_lshl_add_u64 v[128:129], v[128:129], 0, v[130:131]
	global_load_dwordx4 v[180:183], v[128:129], off offset:16
	global_load_dwordx4 v[184:187], v[128:129], off
	global_load_dwordx4 v[188:191], v[128:129], off offset:528
	global_load_dwordx4 v[192:195], v[128:129], off offset:512
	s_nop 4
	v_lshlrev_b32_e32 v249, 12, v166
	v_lshl_add_u32 v249, v132, 2, v249
	global_load_dword v255, v249, s[4:5]
	global_load_dword v255, v249, s[4:5] offset:512
	v_add_u32_e32 v250, 0x10000, v249
	global_load_dword v255, v250, s[4:5]
	global_load_dword v255, v250, s[4:5] offset:512
	v_add_u32_e32 v250, 0x20000, v249
	global_load_dword v255, v250, s[4:5]
	global_load_dword v255, v250, s[4:5] offset:512
	v_add_u32_e32 v250, 0x30000, v249
	global_load_dword v255, v250, s[4:5]
	global_load_dword v255, v250, s[4:5] offset:512
	v_add_u32_e32 v250, 0x80000, v249
	global_load_dword v255, v250, s[4:5]
	global_load_dword v255, v250, s[4:5] offset:512
	v_add_u32_e32 v250, 0x90000, v249
	global_load_dword v255, v250, s[4:5]
	global_load_dword v255, v250, s[4:5] offset:512
	v_add_u32_e32 v250, 0xa0000, v249
	global_load_dword v255, v250, s[4:5]
	global_load_dword v255, v250, s[4:5] offset:512
	v_add_u32_e32 v250, 0xb0000, v249
	global_load_dword v255, v250, s[4:5]
	global_load_dword v255, v250, s[4:5] offset:512
	v_lshl_add_u64 v[178:179], s[4:5], 0, v[130:131]
	v_lshlrev_b64 v[128:129], 12, v[172:173]
	v_lshl_add_u64 v[176:177], v[132:133], 1, s[58:59]
	v_lshl_add_u64 v[132:133], v[178:179], 0, v[128:129]
	s_waitcnt lgkmcnt(0)
	global_load_dwordx4 v[136:139], v[132:133], off offset:16
	global_load_dwordx4 v[140:143], v[132:133], off
	global_load_dwordx4 v[128:131], v[132:133], off offset:528
	s_nop 0
	global_load_dwordx4 v[132:135], v[132:133], off offset:512
	v_lshl_add_u64 v[174:175], v[176:177], 0, v[174:175]
	v_ashrrev_i32_e32 v171, 31, v170
	v_lshlrev_b64 v[172:173], 11, v[172:173]
	v_lshl_add_u64 v[172:173], v[176:177], 0, v[172:173]
	v_ashrrev_i32_e32 v169, 31, v168
	v_readlane_b32 s18, v248, 14
	v_readlane_b32 s19, v248, 15
	v_readlane_b32 s18, v246, 41
	v_readlane_b32 s19, v246, 42
	v_readlane_b32 s6, v248, 2
	v_readlane_b32 s7, v248, 3
	v_readlane_b32 s8, v248, 4
	v_readlane_b32 s9, v248, 5
	v_readlane_b32 s10, v248, 6
	v_readlane_b32 s11, v248, 7
	v_readlane_b32 s12, v248, 8
	v_readlane_b32 s13, v248, 9
	v_readlane_b32 s14, v248, 10
	v_readlane_b32 s15, v248, 11
	v_readlane_b32 s16, v248, 12
	v_readlane_b32 s17, v248, 13
	s_waitcnt vmcnt(0)
	v_pk_add_f32 v[180:181], v[120:121], v[180:181]
	v_pk_add_f32 v[126:127], v[126:127], v[186:187]
	v_pk_add_f32 v[124:125], v[124:125], v[184:185]
	v_pk_add_f32 v[182:183], v[122:123], v[182:183]
	v_cvt_pk_bf16_f32 v120, v124, v125
	v_cvt_pk_bf16_f32 v121, v126, v127
	v_cvt_pk_bf16_f32 v122, v180, v181
	v_pk_add_f32 v[118:119], v[118:119], v[194:195]
	v_cvt_pk_bf16_f32 v123, v182, v183
	global_store_dwordx4 v[174:175], v[120:123], off
	v_pk_add_f32 v[116:117], v[116:117], v[192:193]
	v_pk_add_f32 v[110:111], v[110:111], v[142:143]
	v_mul_f32_e32 v120, v125, v125
	v_mul_f32_e32 v121, v127, v127
	v_fmac_f32_e32 v120, v124, v124
	v_fmac_f32_e32 v121, v126, v126
	v_add_f32_e32 v120, v120, v121
	v_mul_f32_e32 v121, v181, v181
	v_mul_f32_e32 v122, v183, v183
	v_fmac_f32_e32 v121, v180, v180
	v_fmac_f32_e32 v122, v182, v182
	v_add_f32_e32 v121, v121, v122
	v_pk_add_f32 v[122:123], v[112:113], v[188:189]
	v_cvt_pk_bf16_f32 v112, v116, v117
	v_cvt_pk_bf16_f32 v113, v118, v119
	v_add_f32_e32 v124, v120, v121
	v_pk_add_f32 v[120:121], v[114:115], v[190:191]
	v_cvt_pk_bf16_f32 v114, v122, v123
	v_pk_add_f32 v[108:109], v[108:109], v[140:141]
	v_cvt_pk_bf16_f32 v115, v120, v121
	global_store_dwordx4 v[174:175], v[112:115], off offset:256
	v_pk_add_f32 v[136:137], v[104:105], v[136:137]
	v_pk_add_f32 v[138:139], v[106:107], v[138:139]
	v_mul_f32_e32 v112, v117, v117
	v_mul_f32_e32 v113, v119, v119
	v_fmac_f32_e32 v112, v116, v116
	v_fmac_f32_e32 v113, v118, v118
	v_add_f32_e32 v112, v112, v113
	v_mul_f32_e32 v113, v123, v123
	v_mul_f32_e32 v114, v121, v121
	v_fmac_f32_e32 v113, v122, v122
	v_fmac_f32_e32 v114, v120, v120
	v_add_f32_e32 v113, v113, v114
	v_and_b32_e32 v114, 64, v209
	v_add_f32_e32 v112, v112, v113
	v_xor_b32_e32 v113, 16, v209
	v_add_u32_e32 v114, 64, v114
	v_cmp_lt_i32_e32 vcc, v113, v114
	v_add_f32_e32 v112, v124, v112
	v_pk_add_f32 v[102:103], v[102:103], v[134:135]
	v_cndmask_b32_e32 v113, v209, v113, vcc
	v_lshlrev_b32_e32 v152, 2, v113
	ds_bpermute_b32 v113, v152, v112
	v_pk_add_f32 v[100:101], v[100:101], v[132:133]
	s_waitcnt lgkmcnt(0)
	v_add_f32_e32 v174, v112, v113
	v_xor_b32_e32 v112, 32, v209
	v_cmp_lt_i32_e32 vcc, v112, v114
	s_nop 1
	v_cndmask_b32_e32 v112, v209, v112, vcc
	v_lshlrev_b32_e32 v180, 2, v112
	v_lshlrev_b64 v[112:113], 12, v[170:171]
	v_lshl_add_u64 v[116:117], v[178:179], 0, v[112:113]
	global_load_dwordx4 v[120:123], v[116:117], off offset:16
	global_load_dwordx4 v[124:127], v[116:117], off
	global_load_dwordx4 v[112:115], v[116:117], off offset:528
	s_nop 0
	global_load_dwordx4 v[116:119], v[116:117], off offset:512
	v_cvt_pk_bf16_f32 v104, v108, v109
	v_cvt_pk_bf16_f32 v105, v110, v111
	v_cvt_pk_bf16_f32 v106, v136, v137
	v_cvt_pk_bf16_f32 v107, v138, v139
	global_store_dwordx4 v[172:173], v[104:107], off
	ds_bpermute_b32 v175, v180, v174
	v_cmp_lt_u32_e32 vcc, 63, v222
	v_mul_f32_e32 v104, v109, v109
	v_mul_f32_e32 v105, v111, v111
	v_fmac_f32_e32 v104, v108, v108
	v_fmac_f32_e32 v105, v110, v110
	v_add_f32_e32 v104, v104, v105
	v_mul_f32_e32 v105, v137, v137
	v_mul_f32_e32 v106, v139, v139
	v_fmac_f32_e32 v105, v136, v136
	v_fmac_f32_e32 v106, v138, v138
	v_add_f32_e32 v105, v105, v106
	v_pk_add_f32 v[106:107], v[96:97], v[128:129]
	v_cvt_pk_bf16_f32 v96, v100, v101
	v_cvt_pk_bf16_f32 v97, v102, v103
	v_add_f32_e32 v108, v104, v105
	v_pk_add_f32 v[104:105], v[98:99], v[130:131]
	v_cvt_pk_bf16_f32 v98, v106, v107
	v_lshlrev_b64 v[130:131], 11, v[170:171]
	v_cvt_pk_bf16_f32 v99, v104, v105
	global_store_dwordx4 v[172:173], v[96:99], off offset:256
	v_lshl_add_u64 v[130:131], v[176:177], 0, v[130:131]
	s_waitcnt vmcnt(5)
; __device__ __forceinline__ unsigned cvt_pk_bf16(float lo, float hi) { unsigned r; asm volatile("v_cvt_pk_bf16_f32 %0, %1, %2" : "=v"(r) : "v"(lo), "v"(hi)); return r; }
; template <bool RD32>
; __device__ __forceinline__ void res_rows(const float* __restrict__ xold32, const bf16_t* __restrict__ xoldb, bf16_t* __restrict__ xb, float* __restrict__ ssq, const f32x4 (&acc)[2][2][4][2], int row0, int col0, int slot) {
;     ...
;     for (int idx = 0; idx < 8; ++idx) {
;         const int ai = idx >> 2, m = idx & 3; const int r = row0 + ai * HALF + m * 16; const size_t off = (size_t)r * D + col0;
;         if (idx < 7) { const int ai2 = (idx + 1) >> 2, m2 = (idx + 1) & 3; const size_t off2 = (size_t)(row0 + ai2 * HALF + m2 * 16) * D + col0;
; #pragma unroll
;             for (int bj = 0; bj < 2; ++bj) ld(off2 + bj * HALF, xo[(idx + 1) & 1][bj][0], xo[(idx + 1) & 1][bj][1]); }
;         float ss = 0.f;
; #pragma unroll
;         for (int bj = 0; bj < 2; ++bj) { const f32x4 x0 = xo[idx & 1][bj][0] + acc[ai][bj][m][0], x1 = xo[idx & 1][bj][1] + acc[ai][bj][m][1];
;             u32x4 w; w.x = cvt_pk_bf16(x0[0], x0[1]); w.y = cvt_pk_bf16(x0[2], x0[3]); w.z = cvt_pk_bf16(x1[0], x1[1]); w.w = cvt_pk_bf16(x1[2], x1[3]);
;             *(u32x4*)(xb + off + bj * HALF) = w;
;             ss += ((x0[0] * x0[0] + x0[1] * x0[1]) + (x0[2] * x0[2] + x0[3] * x0[3])) + ((x1[0] * x1[0] + x1[1] * x1[1]) + (x1[2] * x1[2] + x1[3] * x1[3])); }
;         ss += __shfl_xor(ss, 16); ss += __shfl_xor(ss, 32);
	v_pk_add_f32 v[120:121], v[88:89], v[120:121]
	v_mul_f32_e32 v96, v101, v101
	v_mul_f32_e32 v97, v103, v103
	v_fmac_f32_e32 v96, v100, v100
	v_fmac_f32_e32 v97, v102, v102
	v_add_f32_e32 v96, v96, v97
	v_mul_f32_e32 v97, v107, v107
	v_mul_f32_e32 v98, v105, v105
	v_fmac_f32_e32 v97, v106, v106
	v_fmac_f32_e32 v98, v104, v104
	v_add_f32_e32 v97, v97, v98
	v_add_f32_e32 v96, v96, v97
	v_add_f32_e32 v96, v108, v96
	ds_bpermute_b32 v97, v152, v96
	s_waitcnt vmcnt(4)
	v_pk_add_f32 v[94:95], v[94:95], v[126:127]
	v_pk_add_f32 v[92:93], v[92:93], v[124:125]
	v_pk_add_f32 v[122:123], v[90:91], v[122:123]
	s_waitcnt vmcnt(2)
	v_pk_add_f32 v[86:87], v[86:87], v[118:119]
	s_waitcnt lgkmcnt(0)
	v_add_f32_e32 v129, v96, v97
	v_lshlrev_b64 v[96:97], 12, v[168:169]
	v_lshl_add_u64 v[100:101], v[178:179], 0, v[96:97]
	global_load_dwordx4 v[104:107], v[100:101], off offset:16
	global_load_dwordx4 v[108:111], v[100:101], off
	global_load_dwordx4 v[96:99], v[100:101], off offset:528
	s_nop 0
	global_load_dwordx4 v[100:103], v[100:101], off offset:512
	v_cvt_pk_bf16_f32 v88, v92, v93
	v_cvt_pk_bf16_f32 v89, v94, v95
	v_cvt_pk_bf16_f32 v90, v120, v121
	v_cvt_pk_bf16_f32 v91, v122, v123
	global_store_dwordx4 v[130:131], v[88:91], off
	v_pk_add_f32 v[84:85], v[84:85], v[116:117]
	v_lshlrev_b64 v[116:117], 11, v[168:169]
	v_mul_f32_e32 v88, v93, v93
	v_mul_f32_e32 v89, v95, v95
	v_fmac_f32_e32 v88, v92, v92
	v_fmac_f32_e32 v89, v94, v94
	v_add_f32_e32 v88, v88, v89
	v_mul_f32_e32 v89, v121, v121
	v_mul_f32_e32 v90, v123, v123
	v_fmac_f32_e32 v89, v120, v120
	v_fmac_f32_e32 v90, v122, v122
	v_add_f32_e32 v89, v89, v90
	v_pk_add_f32 v[90:91], v[80:81], v[112:113]
	v_cvt_pk_bf16_f32 v80, v84, v85
	v_cvt_pk_bf16_f32 v81, v86, v87
	v_add_f32_e32 v92, v88, v89
	v_pk_add_f32 v[88:89], v[82:83], v[114:115]
	v_cvt_pk_bf16_f32 v82, v90, v91
	v_add_u32_e32 v112, 0x80, v166
	v_cvt_pk_bf16_f32 v83, v88, v89
	global_store_dwordx4 v[130:131], v[80:83], off offset:256
	v_ashrrev_i32_e32 v113, 31, v112
	v_lshl_add_u64 v[116:117], v[176:177], 0, v[116:117]
	v_mul_f32_e32 v80, v85, v85
	v_mul_f32_e32 v81, v87, v87
	v_fmac_f32_e32 v80, v84, v84
	v_fmac_f32_e32 v81, v86, v86
	v_add_f32_e32 v80, v80, v81
	v_mul_f32_e32 v81, v91, v91
	v_mul_f32_e32 v82, v89, v89
	v_fmac_f32_e32 v81, v90, v90
	v_fmac_f32_e32 v82, v88, v88
	v_add_f32_e32 v81, v81, v82
	v_add_f32_e32 v80, v80, v81
	v_add_f32_e32 v80, v92, v80
	ds_bpermute_b32 v81, v152, v80
	ds_bpermute_b32 v132, v180, v129
	s_waitcnt lgkmcnt(1)
	v_add_f32_e32 v114, v80, v81
	v_lshlrev_b64 v[80:81], 12, v[112:113]
	v_lshl_add_u64 v[84:85], v[178:179], 0, v[80:81]
	global_load_dwordx4 v[88:91], v[84:85], off offset:16
	global_load_dwordx4 v[92:95], v[84:85], off
	global_load_dwordx4 v[80:83], v[84:85], off offset:528
	s_nop 0
	global_load_dwordx4 v[84:87], v[84:85], off offset:512
	ds_bpermute_b32 v115, v180, v114
	s_waitcnt vmcnt(9)
	v_pk_add_f32 v[104:105], v[72:73], v[104:105]
	s_waitcnt vmcnt(8)
	v_pk_add_f32 v[78:79], v[78:79], v[110:111]
	v_pk_add_f32 v[76:77], v[76:77], v[108:109]
	v_pk_add_f32 v[106:107], v[74:75], v[106:107]
	v_cvt_pk_bf16_f32 v72, v76, v77
	v_cvt_pk_bf16_f32 v73, v78, v79
	v_cvt_pk_bf16_f32 v74, v104, v105
	s_waitcnt vmcnt(6)
	v_pk_add_f32 v[70:71], v[70:71], v[102:103]
	v_cvt_pk_bf16_f32 v75, v106, v107
	global_store_dwordx4 v[116:117], v[72:75], off
	v_pk_add_f32 v[68:69], v[68:69], v[100:101]
	s_waitcnt vmcnt(4)
	v_pk_add_f32 v[88:89], v[56:57], v[88:89]
	v_mul_f32_e32 v72, v77, v77
	v_mul_f32_e32 v73, v79, v79
	v_fmac_f32_e32 v72, v76, v76
	v_fmac_f32_e32 v73, v78, v78
	v_add_f32_e32 v72, v72, v73
	v_mul_f32_e32 v73, v105, v105
	v_mul_f32_e32 v74, v107, v107
	v_fmac_f32_e32 v73, v104, v104
	v_fmac_f32_e32 v74, v106, v106
	v_add_f32_e32 v73, v73, v74
	v_pk_add_f32 v[74:75], v[64:65], v[96:97]
	v_cvt_pk_bf16_f32 v64, v68, v69
	v_cvt_pk_bf16_f32 v65, v70, v71
	v_add_f32_e32 v76, v72, v73
	v_pk_add_f32 v[72:73], v[66:67], v[98:99]
	v_cvt_pk_bf16_f32 v66, v74, v75
	v_add_u32_e32 v96, 0x90, v166
	v_cvt_pk_bf16_f32 v67, v72, v73
	global_store_dwordx4 v[116:117], v[64:67], off offset:256
	v_ashrrev_i32_e32 v97, 31, v96
	v_lshlrev_b64 v[98:99], 11, v[112:113]
	v_mul_f32_e32 v64, v69, v69
	v_mul_f32_e32 v65, v71, v71
	v_fmac_f32_e32 v64, v68, v68
	v_fmac_f32_e32 v65, v70, v70
	v_add_f32_e32 v64, v64, v65
	v_mul_f32_e32 v65, v75, v75
	v_mul_f32_e32 v66, v73, v73
	v_fmac_f32_e32 v65, v74, v74
	v_fmac_f32_e32 v66, v72, v72
	v_add_f32_e32 v65, v65, v66
	v_add_f32_e32 v64, v64, v65
	v_add_f32_e32 v64, v76, v64
	ds_bpermute_b32 v65, v152, v64
	v_lshl_add_u64 v[98:99], v[176:177], 0, v[98:99]
	s_waitcnt vmcnt(4)
	v_pk_add_f32 v[62:63], v[62:63], v[94:95]
	v_pk_add_f32 v[60:61], v[60:61], v[92:93]
	v_pk_add_f32 v[90:91], v[58:59], v[90:91]
	s_waitcnt lgkmcnt(0)
	v_add_f32_e32 v100, v64, v65
	v_lshlrev_b64 v[64:65], 12, v[96:97]
	v_lshl_add_u64 v[68:69], v[178:179], 0, v[64:65]
	global_load_dwordx4 v[72:75], v[68:69], off offset:16
	global_load_dwordx4 v[76:79], v[68:69], off
	global_load_dwordx4 v[64:67], v[68:69], off offset:528
	s_nop 0
	global_load_dwordx4 v[68:71], v[68:69], off offset:512
	v_cvt_pk_bf16_f32 v56, v60, v61
	v_cvt_pk_bf16_f32 v57, v62, v63
	v_cvt_pk_bf16_f32 v58, v88, v89
	v_cvt_pk_bf16_f32 v59, v90, v91
	global_store_dwordx4 v[98:99], v[56:59], off
	s_waitcnt vmcnt(7)
; __device__ __forceinline__ unsigned cvt_pk_bf16(float lo, float hi) { unsigned r; asm volatile("v_cvt_pk_bf16_f32 %0, %1, %2" : "=v"(r) : "v"(lo), "v"(hi)); return r; }
; template <bool RD32>
; __device__ __forceinline__ void res_rows(const float* __restrict__ xold32, const bf16_t* __restrict__ xoldb, bf16_t* __restrict__ xb, float* __restrict__ ssq, const f32x4 (&acc)[2][2][4][2], int row0, int col0, int slot) {
;     ...
;     for (int idx = 0; idx < 8; ++idx) {
;         const int ai = idx >> 2, m = idx & 3; const int r = row0 + ai * HALF + m * 16; const size_t off = (size_t)r * D + col0;
;         if (idx < 7) { const int ai2 = (idx + 1) >> 2, m2 = (idx + 1) & 3; const size_t off2 = (size_t)(row0 + ai2 * HALF + m2 * 16) * D + col0;
; #pragma unroll
;             for (int bj = 0; bj < 2; ++bj) ld(off2 + bj * HALF, xo[(idx + 1) & 1][bj][0], xo[(idx + 1) & 1][bj][1]); }
;         float ss = 0.f;
; #pragma unroll
;         for (int bj = 0; bj < 2; ++bj) { const f32x4 x0 = xo[idx & 1][bj][0] + acc[ai][bj][m][0], x1 = xo[idx & 1][bj][1] + acc[ai][bj][m][1];
;             u32x4 w; w.x = cvt_pk_bf16(x0[0], x0[1]); w.y = cvt_pk_bf16(x0[2], x0[3]); w.z = cvt_pk_bf16(x1[0], x1[1]); w.w = cvt_pk_bf16(x1[2], x1[3]);
;             *(u32x4*)(xb + off + bj * HALF) = w;
;             ss += ((x0[0] * x0[0] + x0[1] * x0[1]) + (x0[2] * x0[2] + x0[3] * x0[3])) + ((x1[0] * x1[0] + x1[1] * x1[1]) + (x1[2] * x1[2] + x1[3] * x1[3])); }
;         ss += __shfl_xor(ss, 16); ss += __shfl_xor(ss, 32);
;         ssv[idx] = ss;
;     }
;     const int fq = slot >> 6;
; #pragma unroll
;     for (int j = 0; j < 2; ++j) { const float v = fq == 0 ? ssv[j] : fq == 1 ? ssv[2 + j] : fq == 2 ? ssv[4 + j] : ssv[6 + j]; const int idx = 2 * fq + j;
;         ssq[(size_t)(row0 + (idx >> 2) * HALF + (idx & 3) * 16) * 16 + (slot & 15)] = v; }
	v_pk_add_f32 v[54:55], v[54:55], v[86:87]
	v_pk_add_f32 v[52:53], v[52:53], v[84:85]
	v_mul_f32_e32 v56, v61, v61
	v_mul_f32_e32 v57, v63, v63
	v_fmac_f32_e32 v56, v60, v60
	v_fmac_f32_e32 v57, v62, v62
	v_add_f32_e32 v56, v56, v57
	v_mul_f32_e32 v57, v89, v89
	v_mul_f32_e32 v58, v91, v91
	v_fmac_f32_e32 v57, v88, v88
	v_fmac_f32_e32 v58, v90, v90
	v_add_f32_e32 v57, v57, v58
	v_pk_add_f32 v[58:59], v[48:49], v[80:81]
	v_cvt_pk_bf16_f32 v48, v52, v53
	v_cvt_pk_bf16_f32 v49, v54, v55
	v_add_f32_e32 v60, v56, v57
	v_pk_add_f32 v[56:57], v[50:51], v[82:83]
	v_cvt_pk_bf16_f32 v50, v58, v59
	v_add_u32_e32 v80, 0xa0, v166
	v_cvt_pk_bf16_f32 v51, v56, v57
	global_store_dwordx4 v[98:99], v[48:51], off offset:256
	v_ashrrev_i32_e32 v81, 31, v80
	v_lshlrev_b64 v[84:85], 11, v[96:97]
	v_mul_f32_e32 v48, v53, v53
	v_mul_f32_e32 v49, v55, v55
	v_fmac_f32_e32 v48, v52, v52
	v_fmac_f32_e32 v49, v54, v54
	v_add_f32_e32 v48, v48, v49
	v_mul_f32_e32 v49, v59, v59
	v_mul_f32_e32 v50, v57, v57
	v_fmac_f32_e32 v49, v58, v58
	v_fmac_f32_e32 v50, v56, v56
	v_add_f32_e32 v49, v49, v50
	v_add_f32_e32 v48, v48, v49
	v_add_f32_e32 v48, v60, v48
	ds_bpermute_b32 v49, v152, v48
	v_lshl_add_u64 v[84:85], v[176:177], 0, v[84:85]
	ds_bpermute_b32 v101, v180, v100
	s_waitcnt lgkmcnt(1)
	v_add_f32_e32 v82, v48, v49
	v_lshlrev_b64 v[48:49], 12, v[80:81]
	v_lshl_add_u64 v[60:61], v[178:179], 0, v[48:49]
	global_load_dwordx4 v[48:51], v[60:61], off offset:16
	global_load_dwordx4 v[52:55], v[60:61], off
	global_load_dwordx4 v[56:59], v[60:61], off offset:528
	s_nop 0
	global_load_dwordx4 v[60:63], v[60:61], off offset:512
	ds_bpermute_b32 v83, v180, v82
	s_waitcnt vmcnt(9)
	v_pk_add_f32 v[72:73], v[40:41], v[72:73]
	s_waitcnt vmcnt(8)
	v_pk_add_f32 v[46:47], v[46:47], v[78:79]
	v_pk_add_f32 v[44:45], v[44:45], v[76:77]
	v_pk_add_f32 v[74:75], v[42:43], v[74:75]
	v_cvt_pk_bf16_f32 v40, v44, v45
	v_cvt_pk_bf16_f32 v41, v46, v47
	v_cvt_pk_bf16_f32 v42, v72, v73
	s_waitcnt vmcnt(6)
	v_pk_add_f32 v[38:39], v[38:39], v[70:71]
	v_cvt_pk_bf16_f32 v43, v74, v75
	global_store_dwordx4 v[84:85], v[40:43], off
	v_pk_add_f32 v[36:37], v[36:37], v[68:69]
	v_lshlrev_b64 v[68:69], 11, v[80:81]
	v_mul_f32_e32 v40, v45, v45
	v_mul_f32_e32 v41, v47, v47
	v_fmac_f32_e32 v40, v44, v44
	v_fmac_f32_e32 v41, v46, v46
	v_add_f32_e32 v40, v40, v41
	v_mul_f32_e32 v41, v73, v73
	v_mul_f32_e32 v42, v75, v75
	v_fmac_f32_e32 v41, v72, v72
	v_fmac_f32_e32 v42, v74, v74
	v_add_f32_e32 v41, v41, v42
	v_pk_add_f32 v[42:43], v[32:33], v[64:65]
	v_cvt_pk_bf16_f32 v32, v36, v37
	v_cvt_pk_bf16_f32 v33, v38, v39
	v_add_f32_e32 v44, v40, v41
	v_pk_add_f32 v[40:41], v[34:35], v[66:67]
	v_cvt_pk_bf16_f32 v34, v42, v43
	v_lshl_add_u64 v[68:69], v[176:177], 0, v[68:69]
	v_cvt_pk_bf16_f32 v35, v40, v41
	global_store_dwordx4 v[84:85], v[32:35], off offset:256
	s_waitcnt vmcnt(5)
	v_pk_add_f32 v[48:49], v[24:25], v[48:49]
	v_mul_f32_e32 v32, v37, v37
	v_mul_f32_e32 v33, v39, v39
	v_fmac_f32_e32 v32, v36, v36
	v_fmac_f32_e32 v33, v38, v38
	v_add_f32_e32 v32, v32, v33
	v_mul_f32_e32 v33, v43, v43
	v_mul_f32_e32 v34, v41, v41
	v_fmac_f32_e32 v33, v42, v42
	v_fmac_f32_e32 v34, v40, v40
	v_add_f32_e32 v33, v33, v34
	v_add_f32_e32 v32, v32, v33
	v_add_f32_e32 v32, v44, v32
	ds_bpermute_b32 v33, v152, v32
	v_add_u32_e32 v44, 0xb0, v166
	v_ashrrev_i32_e32 v45, 31, v44
	s_waitcnt vmcnt(4)
	v_pk_add_f32 v[30:31], v[30:31], v[54:55]
	v_pk_add_f32 v[28:29], v[28:29], v[52:53]
	s_waitcnt lgkmcnt(0)
	v_add_f32_e32 v46, v32, v33
	v_lshlrev_b64 v[32:33], 12, v[44:45]
	v_lshl_add_u64 v[64:65], v[178:179], 0, v[32:33]
	global_load_dwordx4 v[36:39], v[64:65], off offset:16
	global_load_dwordx4 v[40:43], v[64:65], off
	global_load_dwordx4 v[32:35], v[64:65], off offset:528
	s_nop 0
	global_load_dwordx4 v[64:67], v[64:65], off offset:512
	v_cvt_pk_bf16_f32 v24, v28, v29
	v_cvt_pk_bf16_f32 v25, v30, v31
	v_pk_add_f32 v[50:51], v[26:27], v[50:51]
	v_cvt_pk_bf16_f32 v26, v48, v49
	s_waitcnt vmcnt(6)
	v_pk_add_f32 v[22:23], v[22:23], v[62:63]
	v_cvt_pk_bf16_f32 v27, v50, v51
	global_store_dwordx4 v[68:69], v[24:27], off
	v_pk_add_f32 v[20:21], v[20:21], v[60:61]
	ds_bpermute_b32 v47, v180, v46
	v_mul_f32_e32 v24, v29, v29
	v_mul_f32_e32 v25, v31, v31
	v_fmac_f32_e32 v24, v28, v28
	v_fmac_f32_e32 v25, v30, v30
	v_add_f32_e32 v24, v24, v25
	v_mul_f32_e32 v25, v49, v49
	v_mul_f32_e32 v26, v51, v51
	v_fmac_f32_e32 v25, v48, v48
	v_fmac_f32_e32 v26, v50, v50
	v_add_f32_e32 v25, v25, v26
	v_pk_add_f32 v[26:27], v[16:17], v[56:57]
	v_cvt_pk_bf16_f32 v16, v20, v21
	v_cvt_pk_bf16_f32 v17, v22, v23
	v_add_f32_e32 v28, v24, v25
	v_pk_add_f32 v[24:25], v[18:19], v[58:59]
	v_cvt_pk_bf16_f32 v18, v26, v27
	s_waitcnt vmcnt(3)
	v_pk_add_f32 v[14:15], v[14:15], v[42:43]
	v_cvt_pk_bf16_f32 v19, v24, v25
	global_store_dwordx4 v[68:69], v[16:19], off offset:256
	v_pk_add_f32 v[12:13], v[12:13], v[40:41]
	s_waitcnt vmcnt(2)
	v_pk_add_f32 v[6:7], v[6:7], v[66:67]
	v_mul_f32_e32 v16, v21, v21
	v_mul_f32_e32 v17, v23, v23
	v_fmac_f32_e32 v16, v20, v20
	v_fmac_f32_e32 v17, v22, v22
	v_add_f32_e32 v16, v16, v17
	v_mul_f32_e32 v17, v27, v27
	v_mul_f32_e32 v18, v25, v25
	v_fmac_f32_e32 v17, v26, v26
	v_fmac_f32_e32 v18, v24, v24
	v_add_f32_e32 v17, v17, v18
	v_lshlrev_b64 v[18:19], 11, v[44:45]
	v_lshl_add_u64 v[18:19], v[176:177], 0, v[18:19]
	v_pk_add_f32 v[22:23], v[8:9], v[36:37]
	v_cvt_pk_bf16_f32 v8, v12, v13
	v_cvt_pk_bf16_f32 v9, v14, v15
	v_pk_add_f32 v[20:21], v[10:11], v[38:39]
	v_cvt_pk_bf16_f32 v10, v22, v23
	v_pk_add_f32 v[4:5], v[4:5], v[64:65]
	v_cvt_pk_bf16_f32 v11, v20, v21
	global_store_dwordx4 v[18:19], v[8:11], off
	v_add_f32_e32 v16, v16, v17
	v_add_f32_e32 v16, v28, v16
	v_mul_f32_e32 v8, v13, v13
	v_mul_f32_e32 v9, v15, v15
	v_fmac_f32_e32 v8, v12, v12
	v_fmac_f32_e32 v9, v14, v14
	v_add_f32_e32 v8, v8, v9
	v_mul_f32_e32 v9, v23, v23
	v_mul_f32_e32 v10, v21, v21
	v_fmac_f32_e32 v9, v22, v22
	v_fmac_f32_e32 v10, v20, v20
	v_add_f32_e32 v9, v9, v10
	v_pk_add_f32 v[10:11], v[0:1], v[32:33]
	v_cvt_pk_bf16_f32 v0, v4, v5
	v_cvt_pk_bf16_f32 v1, v6, v7
	v_add_f32_e32 v12, v8, v9
	v_pk_add_f32 v[8:9], v[2:3], v[34:35]
	v_cvt_pk_bf16_f32 v2, v10, v11
	ds_bpermute_b32 v17, v152, v16
	v_cvt_pk_bf16_f32 v3, v8, v9
	global_store_dwordx4 v[18:19], v[0:3], off offset:256
	s_waitcnt lgkmcnt(0)
	v_add_f32_e32 v16, v16, v17
	v_mul_f32_e32 v0, v5, v5
	v_mul_f32_e32 v1, v7, v7
	v_fmac_f32_e32 v0, v4, v4
	v_fmac_f32_e32 v1, v6, v6
	v_add_f32_e32 v0, v0, v1
	v_mul_f32_e32 v1, v11, v11
	v_mul_f32_e32 v2, v9, v9
	v_fmac_f32_e32 v1, v10, v10
	v_fmac_f32_e32 v2, v8, v8
	v_add_f32_e32 v1, v1, v2
	v_add_f32_e32 v0, v0, v1
	v_add_f32_e32 v0, v12, v0
	ds_bpermute_b32 v1, v152, v0
	ds_bpermute_b32 v17, v180, v16
	v_and_b32_e32 v2, 0xffffff80, v222
	v_add_u32_e32 v128, v166, v2
	v_and_b32_e32 v2, 15, v223
	s_waitcnt lgkmcnt(1)
	v_add_f32_e32 v0, v0, v1
	ds_bpermute_b32 v1, v180, v0
	v_lshlrev_b32_e32 v152, 2, v2
	v_lshl_add_u64 v[130:131], s[18:19], 0, v[152:153]
	s_and_saveexec_b64 s[4:5], vcc
	s_xor_b64 s[24:25], exec, s[4:5]
	s_cbranch_execz .LBB0_448
; template <bool RD32>
; __device__ __forceinline__ void res_rows(const float* __restrict__ xold32, const bf16_t* __restrict__ xoldb, bf16_t* __restrict__ xb, float* __restrict__ ssq, const f32x4 (&acc)[2][2][4][2], int row0, int col0, int slot) {
;     ...
;     const int fq = slot >> 6;
; #pragma unroll
;     for (int j = 0; j < 2; ++j) { const float v = fq == 0 ? ssv[j] : fq == 1 ? ssv[2 + j] : fq == 2 ? ssv[4 + j] : ssv[6 + j]; const int idx = 2 * fq + j;
;         ssq[(size_t)(row0 + (idx >> 2) * HALF + (idx & 3) * 16) * 16 + (slot & 15)] = v; }
	v_ashrrev_i32_e32 v2, 6, v222
	v_cmp_lt_i32_e32 vcc, 1, v2
	s_mov_b64 s[36:37], 0
	s_and_saveexec_b64 s[4:5], vcc
	s_xor_b64 s[38:39], exec, s[4:5]
	s_cbranch_execnz .LBB0_461
	s_or_saveexec_b64 s[38:39], s[38:39]
	v_cmp_ne_u32_e32 vcc, 1, v2
	s_xor_b64 exec, exec, s[38:39]
	s_cbranch_execnz .LBB0_464

; __device__ __forceinline__ unsigned cvt_pk_bf16(float lo, float hi) { unsigned r; asm volatile("v_cvt_pk_bf16_f32 %0, %1, %2" : "=v"(r) : "v"(lo), "v"(hi)); return r; }
; __device__ __forceinline__ float bflo(unsigned w) { return __uint_as_float(w << 16); }
; __device__ __forceinline__ float bfhi(unsigned w) { return __uint_as_float(w & 0xffff0000u); }
; template <bool RD32>
; __device__ __forceinline__ void res_rows(const float* __restrict__ xold32, const bf16_t* __restrict__ xoldb, bf16_t* __restrict__ xb, float* __restrict__ ssq, const f32x4 (&acc)[2][2][4][2], int row0, int col0, int slot) {
;     f32x4 xo[2][2][2];
;     float ssv[8];
;     auto ld = [&](size_t o, f32x4& a, f32x4& b) { if (RD32) { a = *(const f32x4*)(xold32 + o); b = *(const f32x4*)(xold32 + o + 4); }
;         else { const u32x4 w = *(const u32x4*)(xoldb + o); a = (f32x4){bflo(w.x), bfhi(w.x), bflo(w.y), bfhi(w.y)}; b = (f32x4){bflo(w.z), bfhi(w.z), bflo(w.w), bfhi(w.w)}; } };
; #pragma unroll
;     for (int bj = 0; bj < 2; ++bj) ld((size_t)row0 * D + col0 + bj * HALF, xo[0][bj][0], xo[0][bj][1]);
; #pragma unroll
;     for (int idx = 0; idx < 8; ++idx) {
;         const int ai = idx >> 2, m = idx & 3; const int r = row0 + ai * HALF + m * 16; const size_t off = (size_t)r * D + col0;
;         if (idx < 7) { const int ai2 = (idx + 1) >> 2, m2 = (idx + 1) & 3; const size_t off2 = (size_t)(row0 + ai2 * HALF + m2 * 16) * D + col0;
; #pragma unroll
;             for (int bj = 0; bj < 2; ++bj) ld(off2 + bj * HALF, xo[(idx + 1) & 1][bj][0], xo[(idx + 1) & 1][bj][1]); }
;         float ss = 0.f;
; #pragma unroll
;         for (int bj = 0; bj < 2; ++bj) { const f32x4 x0 = xo[idx & 1][bj][0] + acc[ai][bj][m][0], x1 = xo[idx & 1][bj][1] + acc[ai][bj][m][1];
;             u32x4 w; w.x = cvt_pk_bf16(x0[0], x0[1]); w.y = cvt_pk_bf16(x0[2], x0[3]); w.z = cvt_pk_bf16(x1[0], x1[1]); w.w = cvt_pk_bf16(x1[2], x1[3]);
;             *(u32x4*)(xb + off + bj * HALF) = w;
;             ss += ((x0[0] * x0[0] + x0[1] * x0[1]) + (x0[2] * x0[2] + x0[3] * x0[3])) + ((x1[0] * x1[0] + x1[1] * x1[1]) + (x1[2] * x1[2] + x1[3] * x1[3])); }
;         ss += __shfl_xor(ss, 16); ss += __shfl_xor(ss, 32);
;         ssv[idx] = ss;
.LBB0_615:
	v_lshl_add_u32 v164, s51, 8, v174
	v_lshl_or_b32 v128, s50, 8, v176
	v_lshlrev_b32_e32 v249, 11, v164
	v_lshl_add_u32 v249, v128, 1, v249
	global_load_dword v255, v249, s[58:59]
	global_load_dword v255, v249, s[58:59] offset:256
	v_add_u32_e32 v250, 0x8000, v249
	global_load_dword v255, v250, s[58:59]
	global_load_dword v255, v250, s[58:59] offset:256
	v_add_u32_e32 v250, 0x10000, v249
	global_load_dword v255, v250, s[58:59]
	global_load_dword v255, v250, s[58:59] offset:256
	v_add_u32_e32 v250, 0x18000, v249
	global_load_dword v255, v250, s[58:59]
	global_load_dword v255, v250, s[58:59] offset:256
	v_add_u32_e32 v250, 0x40000, v249
	global_load_dword v255, v250, s[58:59]
	global_load_dword v255, v250, s[58:59] offset:256
	v_add_u32_e32 v250, 0x48000, v249
	global_load_dword v255, v250, s[58:59]
	global_load_dword v255, v250, s[58:59] offset:256
	v_add_u32_e32 v250, 0x50000, v249
	global_load_dword v255, v250, s[58:59]
	global_load_dword v255, v250, s[58:59] offset:256
	v_add_u32_e32 v250, 0x58000, v249
	global_load_dword v255, v250, s[58:59]
	global_load_dword v255, v250, s[58:59] offset:256
	v_ashrrev_i32_e32 v165, 31, v164
	v_ashrrev_i32_e32 v129, 31, v128
	v_lshlrev_b64 v[166:167], 11, v[164:165]
	v_lshl_add_u64 v[130:131], s[58:59], 0, v[166:167]
	v_lshlrev_b64 v[128:129], 1, v[128:129]
	v_lshl_add_u64 v[130:131], v[130:131], 0, v[128:129]
	global_load_dwordx4 v[136:139], v[130:131], off
	global_load_dwordx4 v[140:143], v[130:131], off offset:256
	v_or_b32_e32 v130, 16, v164
	v_ashrrev_i32_e32 v131, 31, v130
	v_lshl_add_u64 v[168:169], s[58:59], 0, v[128:129]
	v_lshlrev_b64 v[128:129], 11, v[130:131]
	v_lshl_add_u64 v[170:171], v[168:169], 0, v[128:129]
	global_load_dwordx4 v[128:131], v[170:171], off
	global_load_dwordx4 v[132:135], v[170:171], off offset:256
	v_and_b32_e32 v172, 64, v209
	v_xor_b32_e32 v173, 16, v209
	v_add_u32_e32 v194, 64, v172
	v_or_b32_e32 v172, 32, v164
	v_or_b32_e32 v182, 48, v164
	v_cmp_lt_i32_e32 vcc, v173, v194
	v_ashrrev_i32_e32 v183, 31, v182
	v_lshlrev_b64 v[182:183], 11, v[182:183]
	v_cndmask_b32_e32 v180, v209, v173, vcc
	v_ashrrev_i32_e32 v173, 31, v172
	v_lshlrev_b64 v[172:173], 11, v[172:173]
	v_lshl_add_u64 v[166:167], v[168:169], 0, v[166:167]
	v_lshl_add_u64 v[172:173], v[168:169], 0, v[172:173]
	v_lshl_add_u64 v[168:169], v[168:169], 0, v[182:183]
	v_lshlrev_b32_e32 v180, 2, v180
	s_mov_b32 s14, 0x40000
	v_xor_b32_e32 v181, 32, v209
	s_lshl_b32 s29, s50, 2
	v_or_b32_e32 v179, s29, v177
	s_waitcnt vmcnt(0)
	v_lshlrev_b32_e32 v182, 16, v136
	v_and_b32_e32 v183, 0xffff0000, v136
	v_lshlrev_b32_e32 v136, 16, v137
	v_and_b32_e32 v137, 0xffff0000, v137
	v_lshlrev_b32_e32 v184, 16, v138
	v_and_b32_e32 v185, 0xffff0000, v138
	v_lshlrev_b32_e32 v138, 16, v139
	v_and_b32_e32 v139, 0xffff0000, v139
	v_lshlrev_b32_e32 v188, 16, v142
	v_and_b32_e32 v189, 0xffff0000, v142
	v_lshlrev_b32_e32 v142, 16, v143
	v_and_b32_e32 v143, 0xffff0000, v143
	v_lshlrev_b32_e32 v186, 16, v140
	v_and_b32_e32 v187, 0xffff0000, v140
	v_lshlrev_b32_e32 v140, 16, v141
	v_and_b32_e32 v141, 0xffff0000, v141
	v_pk_add_f32 v[126:127], v[126:127], v[136:137]
	v_pk_add_f32 v[124:125], v[124:125], v[182:183]
	v_pk_add_f32 v[136:137], v[122:123], v[138:139]
	v_pk_add_f32 v[138:139], v[120:121], v[184:185]
	v_pk_add_f32 v[142:143], v[110:111], v[142:143]
	v_pk_add_f32 v[184:185], v[108:109], v[188:189]
	v_cvt_pk_bf16_f32 v108, v124, v125
	v_cvt_pk_bf16_f32 v109, v126, v127
	v_cvt_pk_bf16_f32 v110, v138, v139
	v_cvt_pk_bf16_f32 v111, v136, v137
	v_pk_add_f32 v[140:141], v[118:119], v[140:141]
	v_pk_add_f32 v[182:183], v[116:117], v[186:187]
	global_store_dwordx4 v[166:167], v[108:111], off
	v_lshlrev_b32_e32 v190, 16, v128
	v_and_b32_e32 v191, 0xffff0000, v128
	v_cvt_pk_bf16_f32 v108, v182, v183
	v_cvt_pk_bf16_f32 v109, v140, v141
	v_cvt_pk_bf16_f32 v110, v184, v185
	v_cvt_pk_bf16_f32 v111, v142, v143
	global_load_dwordx4 v[116:119], v[172:173], off
	global_load_dwordx4 v[120:123], v[172:173], off offset:256
	v_lshlrev_b32_e32 v128, 16, v129
	v_and_b32_e32 v129, 0xffff0000, v129
	v_lshlrev_b32_e32 v186, 16, v130
	v_and_b32_e32 v187, 0xffff0000, v130
	v_lshlrev_b32_e32 v130, 16, v131
	v_and_b32_e32 v131, 0xffff0000, v131
	v_lshlrev_b32_e32 v188, 16, v132
	v_and_b32_e32 v189, 0xffff0000, v132
	v_lshlrev_b32_e32 v192, 16, v134
	v_and_b32_e32 v193, 0xffff0000, v134
	v_lshlrev_b32_e32 v134, 16, v135
	v_and_b32_e32 v135, 0xffff0000, v135
	v_lshlrev_b32_e32 v132, 16, v133
	v_and_b32_e32 v133, 0xffff0000, v133
	v_pk_add_f32 v[114:115], v[114:115], v[128:129]
	v_pk_add_f32 v[112:113], v[112:113], v[190:191]
	v_pk_add_f32 v[128:129], v[106:107], v[130:131]
	v_pk_add_f32 v[130:131], v[104:105], v[186:187]
	v_pk_add_f32 v[186:187], v[100:101], v[188:189]
	v_pk_add_f32 v[134:135], v[98:99], v[134:135]
	v_pk_add_f32 v[188:189], v[96:97], v[192:193]
	global_store_dwordx4 v[166:167], v[108:111], off offset:256
	v_cvt_pk_bf16_f32 v96, v112, v113
	v_cvt_pk_bf16_f32 v97, v114, v115
	v_cvt_pk_bf16_f32 v98, v130, v131
	v_cvt_pk_bf16_f32 v99, v128, v129
	v_pk_add_f32 v[132:133], v[102:103], v[132:133]
	global_store_dwordx4 v[170:171], v[96:99], off
	v_mul_f32_e32 v125, v125, v125
	v_mul_f32_e32 v127, v127, v127
	v_cvt_pk_bf16_f32 v96, v186, v187
	v_cvt_pk_bf16_f32 v97, v132, v133
	v_cvt_pk_bf16_f32 v98, v188, v189
	v_cvt_pk_bf16_f32 v99, v134, v135
	global_load_dwordx4 v[100:103], v[168:169], off
	global_load_dwordx4 v[104:107], v[168:169], off offset:256
	v_mul_f32_e32 v139, v139, v139
	v_mul_f32_e32 v137, v137, v137
	v_mul_f32_e32 v183, v183, v183
	v_mul_f32_e32 v141, v141, v141
	v_mul_f32_e32 v185, v185, v185
	v_mul_f32_e32 v143, v143, v143
	v_fmac_f32_e32 v125, v124, v124
	v_fmac_f32_e32 v127, v126, v126
	v_fmac_f32_e32 v139, v138, v138
	v_fmac_f32_e32 v137, v136, v136
	v_fmac_f32_e32 v183, v182, v182
	v_fmac_f32_e32 v141, v140, v140
	v_fmac_f32_e32 v185, v184, v184
	v_fmac_f32_e32 v143, v142, v142
	v_add_f32_e32 v108, v125, v127
	v_add_f32_e32 v109, v139, v137
	v_add_f32_e32 v110, v183, v141
	v_add_f32_e32 v111, v185, v143
	v_add_f32_e32 v108, v108, v109
	v_add_f32_e32 v109, v110, v111
	v_mul_f32_e32 v190, v113, v113
	v_mul_f32_e32 v191, v115, v115
	v_mul_f32_e32 v192, v131, v131
	v_mul_f32_e32 v193, v129, v129
	v_add_f32_e32 v108, v108, v109
	v_fmac_f32_e32 v190, v112, v112
	v_fmac_f32_e32 v191, v114, v114
	v_fmac_f32_e32 v192, v130, v130
	v_fmac_f32_e32 v193, v128, v128
	ds_bpermute_b32 v109, v180, v108
	v_add_f32_e32 v112, v190, v191
	v_add_f32_e32 v110, v192, v193
	v_add_f32_e32 v127, v112, v110
	v_mul_f32_e32 v195, v187, v187
	v_mul_f32_e32 v196, v133, v133
	v_mul_f32_e32 v197, v189, v189
	v_fmac_f32_e32 v195, v186, v186
	v_fmac_f32_e32 v196, v132, v132
	v_fmac_f32_e32 v197, v188, v188
	v_add_f32_e32 v126, v195, v196
	global_store_dwordx4 v[170:171], v[96:99], off offset:256
	s_waitcnt vmcnt(6)
; __device__ __forceinline__ unsigned cvt_pk_bf16(float lo, float hi) { unsigned r; asm volatile("v_cvt_pk_bf16_f32 %0, %1, %2" : "=v"(r) : "v"(lo), "v"(hi)); return r; }
; template <bool RD32>
; __device__ __forceinline__ void res_rows(const float* __restrict__ xold32, const bf16_t* __restrict__ xoldb, bf16_t* __restrict__ xb, float* __restrict__ ssq, const f32x4 (&acc)[2][2][4][2], int row0, int col0, int slot) {
;     ...
;     for (int idx = 0; idx < 8; ++idx) {
;         const int ai = idx >> 2, m = idx & 3; const int r = row0 + ai * HALF + m * 16; const size_t off = (size_t)r * D + col0;
;         if (idx < 7) { const int ai2 = (idx + 1) >> 2, m2 = (idx + 1) & 3; const size_t off2 = (size_t)(row0 + ai2 * HALF + m2 * 16) * D + col0;
; #pragma unroll
;             for (int bj = 0; bj < 2; ++bj) ld(off2 + bj * HALF, xo[(idx + 1) & 1][bj][0], xo[(idx + 1) & 1][bj][1]); }
;         float ss = 0.f;
; #pragma unroll
;         for (int bj = 0; bj < 2; ++bj) { const f32x4 x0 = xo[idx & 1][bj][0] + acc[ai][bj][m][0], x1 = xo[idx & 1][bj][1] + acc[ai][bj][m][1];
;             u32x4 w; w.x = cvt_pk_bf16(x0[0], x0[1]); w.y = cvt_pk_bf16(x0[2], x0[3]); w.z = cvt_pk_bf16(x1[0], x1[1]); w.w = cvt_pk_bf16(x1[2], x1[3]);
;             *(u32x4*)(xb + off + bj * HALF) = w;
;             ss += ((x0[0] * x0[0] + x0[1] * x0[1]) + (x0[2] * x0[2] + x0[3] * x0[3])) + ((x1[0] * x1[0] + x1[1] * x1[1]) + (x1[2] * x1[2] + x1[3] * x1[3])); }
;         ss += __shfl_xor(ss, 16); ss += __shfl_xor(ss, 32);
	v_lshlrev_b32_e32 v110, 16, v118
	v_and_b32_e32 v111, 0xffff0000, v118
	v_lshlrev_b32_e32 v112, 16, v119
	v_and_b32_e32 v113, 0xffff0000, v119
	s_waitcnt vmcnt(5)
	v_lshlrev_b32_e32 v118, 16, v122
	v_and_b32_e32 v119, 0xffff0000, v122
	v_pk_add_f32 v[118:119], v[80:81], v[118:119]
	v_mul_f32_e32 v80, v135, v135
	v_fmac_f32_e32 v80, v134, v134
	s_waitcnt lgkmcnt(0)
	v_add_f32_e32 v96, v108, v109
	v_lshlrev_b32_e32 v98, 16, v116
	v_and_b32_e32 v99, 0xffff0000, v116
	v_lshlrev_b32_e32 v108, 16, v117
	v_and_b32_e32 v109, 0xffff0000, v117
	v_lshlrev_b32_e32 v114, 16, v120
	v_and_b32_e32 v115, 0xffff0000, v120
	v_lshlrev_b32_e32 v116, 16, v121
	v_and_b32_e32 v117, 0xffff0000, v121
	v_lshlrev_b32_e32 v120, 16, v123
	v_and_b32_e32 v121, 0xffff0000, v123
	v_add_f32_e32 v80, v197, v80
	v_pk_add_f32 v[120:121], v[82:83], v[120:121]
	v_add_co_u32_e32 v82, vcc, s14, v166
	v_add_f32_e32 v80, v126, v80
	s_mov_b64 s[14:15], 0x40000
	v_pk_add_f32 v[122:123], v[94:95], v[108:109]
	v_pk_add_f32 v[98:99], v[92:93], v[98:99]
	v_pk_add_f32 v[90:91], v[90:91], v[112:113]
	v_pk_add_f32 v[88:89], v[88:89], v[110:111]
	v_cvt_pk_bf16_f32 v92, v98, v99
	v_cvt_pk_bf16_f32 v93, v122, v123
	v_pk_add_f32 v[124:125], v[84:85], v[114:115]
	v_cvt_pk_bf16_f32 v94, v88, v89
	v_cvt_pk_bf16_f32 v95, v90, v91
	v_addc_co_u32_e32 v83, vcc, 0, v167, vcc
	v_add_f32_e32 v84, v127, v80
	v_lshl_add_u64 v[80:81], v[166:167], 0, s[14:15]
	global_store_dwordx4 v[172:173], v[92:95], off
	v_pk_add_f32 v[116:117], v[86:87], v[116:117]
	v_mul_f32_e32 v97, v99, v99
	v_cvt_pk_bf16_f32 v92, v124, v125
	v_cvt_pk_bf16_f32 v93, v116, v117
	v_cvt_pk_bf16_f32 v94, v118, v119
	v_cvt_pk_bf16_f32 v95, v120, v121
	global_load_dwordx4 v[108:111], v[82:83], off
	global_load_dwordx4 v[112:115], v[80:81], off offset:256
	s_waitcnt vmcnt(4)
	v_lshlrev_b32_e32 v132, 16, v106
	v_and_b32_e32 v133, 0xffff0000, v106
	v_fmac_f32_e32 v97, v98, v98
	v_mul_f32_e32 v98, v123, v123
	v_fmac_f32_e32 v98, v122, v122
	v_mul_f32_e32 v89, v89, v89
	v_pk_add_f32 v[122:123], v[64:65], v[132:133]
	v_mul_f32_e32 v64, v91, v91
	v_cmp_lt_i32_e32 vcc, v181, v194
	v_lshlrev_b32_e32 v106, 16, v107
	v_and_b32_e32 v107, 0xffff0000, v107
	s_mov_b32 s14, 0x48000
	v_fmac_f32_e32 v89, v88, v88
	v_fmac_f32_e32 v64, v90, v90
	v_cndmask_b32_e32 v85, v209, v181, vcc
	v_lshlrev_b32_e32 v126, 16, v100
	v_and_b32_e32 v127, 0xffff0000, v100
	v_lshlrev_b32_e32 v100, 16, v101
	v_and_b32_e32 v101, 0xffff0000, v101
	v_lshlrev_b32_e32 v128, 16, v102
	v_and_b32_e32 v129, 0xffff0000, v102
	v_lshlrev_b32_e32 v102, 16, v103
	v_and_b32_e32 v103, 0xffff0000, v103
	v_add_f32_e32 v97, v97, v98
	v_pk_add_f32 v[106:107], v[66:67], v[106:107]
	v_add_co_u32_e32 v66, vcc, s14, v166
	v_add_f32_e32 v64, v89, v64
	s_mov_b64 s[14:15], 0x48000
	v_lshlrev_b32_e32 v130, 16, v104
	v_and_b32_e32 v131, 0xffff0000, v104
	v_lshlrev_b32_e32 v104, 16, v105
	v_and_b32_e32 v105, 0xffff0000, v105
	global_store_dwordx4 v[172:173], v[92:95], off offset:256
	v_pk_add_f32 v[98:99], v[74:75], v[102:103]
	v_addc_co_u32_e32 v67, vcc, 0, v167, vcc
	v_pk_add_f32 v[92:93], v[78:79], v[100:101]
	v_pk_add_f32 v[94:95], v[76:77], v[126:127]
	v_pk_add_f32 v[100:101], v[72:73], v[128:129]
	v_cvt_pk_bf16_f32 v72, v94, v95
	v_cvt_pk_bf16_f32 v73, v92, v93
	v_add_f32_e32 v88, v97, v64
	v_cvt_pk_bf16_f32 v74, v100, v101
	v_cvt_pk_bf16_f32 v75, v98, v99
	v_lshl_add_u64 v[64:65], v[166:167], 0, s[14:15]
	global_store_dwordx4 v[168:169], v[72:75], off
	v_pk_add_f32 v[102:103], v[70:71], v[104:105]
	v_pk_add_f32 v[104:105], v[68:69], v[130:131]
	v_mul_f32_e32 v89, v125, v125
	v_cvt_pk_bf16_f32 v68, v104, v105
	v_cvt_pk_bf16_f32 v69, v102, v103
	v_cvt_pk_bf16_f32 v70, v122, v123
	v_cvt_pk_bf16_f32 v71, v106, v107
	global_load_dwordx4 v[72:75], v[66:67], off
	global_load_dwordx4 v[76:79], v[64:65], off offset:256
	v_mul_f32_e32 v90, v117, v117
	v_fmac_f32_e32 v89, v124, v124
	v_fmac_f32_e32 v90, v116, v116
	v_add_f32_e32 v89, v89, v90
	v_mul_f32_e32 v90, v119, v119
	v_mul_f32_e32 v91, v121, v121
	v_mul_f32_e32 v95, v95, v95
	v_mul_f32_e32 v93, v93, v93
	v_fmac_f32_e32 v90, v118, v118
	v_fmac_f32_e32 v91, v120, v120
	v_fmac_f32_e32 v95, v94, v94
	v_fmac_f32_e32 v93, v92, v92
	v_add_f32_e32 v90, v90, v91
	v_add_f32_e32 v92, v95, v93
	v_mul_f32_e32 v93, v101, v101
	v_mul_f32_e32 v94, v99, v99
	v_add_f32_e32 v89, v89, v90
	v_fmac_f32_e32 v93, v100, v100
	v_fmac_f32_e32 v94, v98, v98
	global_store_dwordx4 v[168:169], v[68:71], off offset:256
	s_mov_b32 s14, 0x50000
	v_add_f32_e32 v97, v88, v89
	v_mul_f32_e32 v68, v105, v105
	s_waitcnt vmcnt(5)
	v_lshlrev_b32_e32 v118, 16, v114
	v_and_b32_e32 v119, 0xffff0000, v114
	v_lshlrev_b32_e32 v114, 16, v115
	v_and_b32_e32 v115, 0xffff0000, v115
	v_mul_f32_e32 v69, v103, v103
	v_lshlrev_b32_e32 v88, 16, v108
	v_and_b32_e32 v89, 0xffff0000, v108
	v_lshlrev_b32_e32 v90, 16, v109
	v_and_b32_e32 v91, 0xffff0000, v109
	v_lshlrev_b32_e32 v108, 16, v110
	v_and_b32_e32 v109, 0xffff0000, v110
	v_lshlrev_b32_e32 v110, 16, v111
	v_and_b32_e32 v111, 0xffff0000, v111
	v_add_f32_e32 v93, v93, v94
	v_fmac_f32_e32 v68, v104, v104
	v_fmac_f32_e32 v69, v102, v102
	v_pk_add_f32 v[94:95], v[50:51], v[114:115]
	v_add_co_u32_e32 v50, vcc, s14, v166
	v_lshlrev_b32_e32 v116, 16, v112
	v_and_b32_e32 v117, 0xffff0000, v112
	v_lshlrev_b32_e32 v112, 16, v113
	v_and_b32_e32 v113, 0xffff0000, v113
	v_add_f32_e32 v124, v68, v69
	v_pk_add_f32 v[62:63], v[62:63], v[90:91]
	v_pk_add_f32 v[60:61], v[60:61], v[88:89]
	v_pk_add_f32 v[58:59], v[58:59], v[110:111]
	v_pk_add_f32 v[56:57], v[56:57], v[108:109]
	v_cvt_pk_bf16_f32 v68, v60, v61
	v_cvt_pk_bf16_f32 v69, v62, v63
	v_addc_co_u32_e32 v51, vcc, 0, v167, vcc
	v_cvt_pk_bf16_f32 v70, v56, v57
	v_cvt_pk_bf16_f32 v71, v58, v59
	v_add_f32_e32 v121, v92, v93
	global_store_dwordx4 v[82:83], v[68:71], off
	v_pk_add_f32 v[82:83], v[54:55], v[112:113]
	v_pk_add_f32 v[92:93], v[52:53], v[116:117]
	v_pk_add_f32 v[98:99], v[48:49], v[118:119]
	v_cvt_pk_bf16_f32 v52, v92, v93
	v_cvt_pk_bf16_f32 v53, v82, v83
	s_mov_b64 s[14:15], 0x50000
	v_cvt_pk_bf16_f32 v54, v98, v99
	v_cvt_pk_bf16_f32 v55, v94, v95
	global_load_dwordx4 v[68:71], v[50:51], off
	v_lshl_add_u64 v[48:49], v[166:167], 0, s[14:15]
	global_load_dwordx4 v[88:91], v[48:49], off offset:256
	s_mov_b32 s14, 0x58000
	v_mul_f32_e32 v108, v107, v107
	v_fmac_f32_e32 v108, v106, v106
	global_store_dwordx4 v[80:81], v[52:55], off offset:256
	v_mul_f32_e32 v123, v123, v123
	v_fmac_f32_e32 v123, v122, v122
	ds_bpermute_b32 v86, v180, v84
	ds_bpermute_b32 v120, v180, v97
	s_waitcnt vmcnt(6)
; __device__ __forceinline__ unsigned cvt_pk_bf16(float lo, float hi) { unsigned r; asm volatile("v_cvt_pk_bf16_f32 %0, %1, %2" : "=v"(r) : "v"(lo), "v"(hi)); return r; }
; template <bool RD32>
; __device__ __forceinline__ void res_rows(const float* __restrict__ xold32, const bf16_t* __restrict__ xoldb, bf16_t* __restrict__ xb, float* __restrict__ ssq, const f32x4 (&acc)[2][2][4][2], int row0, int col0, int slot) {
;     ...
;     for (int idx = 0; idx < 8; ++idx) {
;         const int ai = idx >> 2, m = idx & 3; const int r = row0 + ai * HALF + m * 16; const size_t off = (size_t)r * D + col0;
;         if (idx < 7) { const int ai2 = (idx + 1) >> 2, m2 = (idx + 1) & 3; const size_t off2 = (size_t)(row0 + ai2 * HALF + m2 * 16) * D + col0;
; #pragma unroll
;             for (int bj = 0; bj < 2; ++bj) ld(off2 + bj * HALF, xo[(idx + 1) & 1][bj][0], xo[(idx + 1) & 1][bj][1]); }
;         float ss = 0.f;
; #pragma unroll
;         for (int bj = 0; bj < 2; ++bj) { const f32x4 x0 = xo[idx & 1][bj][0] + acc[ai][bj][m][0], x1 = xo[idx & 1][bj][1] + acc[ai][bj][m][1];
;             u32x4 w; w.x = cvt_pk_bf16(x0[0], x0[1]); w.y = cvt_pk_bf16(x0[2], x0[3]); w.z = cvt_pk_bf16(x1[0], x1[1]); w.w = cvt_pk_bf16(x1[2], x1[3]);
;             *(u32x4*)(xb + off + bj * HALF) = w;
;             ss += ((x0[0] * x0[0] + x0[1] * x0[1]) + (x0[2] * x0[2] + x0[3] * x0[3])) + ((x1[0] * x1[0] + x1[1] * x1[1]) + (x1[2] * x1[2] + x1[3] * x1[3])); }
;         ss += __shfl_xor(ss, 16); ss += __shfl_xor(ss, 32);
	v_lshlrev_b32_e32 v100, 16, v72
	s_waitcnt vmcnt(5)
	v_lshlrev_b32_e32 v104, 16, v76
	v_and_b32_e32 v105, 0xffff0000, v76
	v_and_b32_e32 v101, 0xffff0000, v72
	v_lshlrev_b32_e32 v72, 16, v73
	v_and_b32_e32 v73, 0xffff0000, v73
	v_lshlrev_b32_e32 v102, 16, v74
	v_and_b32_e32 v103, 0xffff0000, v74
	v_lshlrev_b32_e32 v74, 16, v75
	v_and_b32_e32 v75, 0xffff0000, v75
	v_pk_add_f32 v[36:37], v[36:37], v[104:105]
	v_add_co_u32_e32 v104, vcc, s14, v166
	v_lshlrev_b32_e32 v76, 16, v77
	v_and_b32_e32 v77, 0xffff0000, v77
	v_lshlrev_b32_e32 v106, 16, v78
	v_and_b32_e32 v107, 0xffff0000, v78
	v_lshlrev_b32_e32 v78, 16, v79
	v_and_b32_e32 v79, 0xffff0000, v79
	v_pk_add_f32 v[46:47], v[46:47], v[72:73]
	v_pk_add_f32 v[80:81], v[44:45], v[100:101]
	v_pk_add_f32 v[100:101], v[42:43], v[74:75]
	v_pk_add_f32 v[102:103], v[40:41], v[102:103]
	v_cvt_pk_bf16_f32 v40, v80, v81
	v_cvt_pk_bf16_f32 v41, v46, v47
	v_addc_co_u32_e32 v105, vcc, 0, v167, vcc
	v_cvt_pk_bf16_f32 v42, v102, v103
	v_cvt_pk_bf16_f32 v43, v100, v101
	global_store_dwordx4 v[66:67], v[40:43], off
	v_pk_add_f32 v[66:67], v[38:39], v[76:77]
	v_pk_add_f32 v[76:77], v[34:35], v[78:79]
	v_pk_add_f32 v[78:79], v[32:33], v[106:107]
	v_cvt_pk_bf16_f32 v42, v36, v37
	v_cvt_pk_bf16_f32 v43, v66, v67
	v_add_f32_e32 v32, v123, v108
	v_cvt_pk_bf16_f32 v44, v78, v79
	v_cvt_pk_bf16_f32 v45, v76, v77
	global_load_dwordx4 v[52:55], v[104:105], off
	v_add_f32_e32 v32, v124, v32
	s_mov_b64 s[14:15], 0x58000
	v_add_f32_e32 v34, v121, v32
	v_lshl_add_u64 v[32:33], v[166:167], 0, s[14:15]
	global_load_dwordx4 v[72:75], v[32:33], off offset:256
	v_mul_f32_e32 v38, v61, v61
	v_mul_f32_e32 v39, v63, v63
	v_mul_f32_e32 v81, v81, v81
	v_mul_f32_e32 v47, v47, v47
	v_fmac_f32_e32 v38, v60, v60
	v_fmac_f32_e32 v39, v62, v62
	v_fmac_f32_e32 v81, v80, v80
	v_fmac_f32_e32 v47, v46, v46
	v_add_f32_e32 v38, v38, v39
	v_mul_f32_e32 v39, v57, v57
	v_mul_f32_e32 v40, v59, v59
	v_add_f32_e32 v46, v81, v47
	v_mul_f32_e32 v47, v103, v103
	v_mul_f32_e32 v80, v101, v101
	v_mul_f32_e32 v37, v37, v37
	v_fmac_f32_e32 v39, v56, v56
	v_fmac_f32_e32 v40, v58, v58
	v_fmac_f32_e32 v47, v102, v102
	v_fmac_f32_e32 v80, v100, v100
	v_fmac_f32_e32 v37, v36, v36
	v_mul_f32_e32 v36, v67, v67
	v_add_f32_e32 v47, v47, v80
	v_fmac_f32_e32 v36, v66, v66
	global_store_dwordx4 v[64:65], v[42:45], off offset:256
	v_add_f32_e32 v46, v46, v47
	s_waitcnt vmcnt(6)
	v_lshlrev_b32_e32 v56, 16, v68
	v_and_b32_e32 v57, 0xffff0000, v68
	v_lshlrev_b32_e32 v58, 16, v69
	v_and_b32_e32 v59, 0xffff0000, v69
	v_lshlrev_b32_e32 v60, 16, v70
	v_and_b32_e32 v61, 0xffff0000, v70
	v_lshlrev_b32_e32 v62, 16, v71
	v_and_b32_e32 v63, 0xffff0000, v71
	v_pk_add_f32 v[30:31], v[30:31], v[58:59]
	v_pk_add_f32 v[28:29], v[28:29], v[56:57]
	v_pk_add_f32 v[58:59], v[24:25], v[60:61]
	v_cvt_pk_bf16_f32 v24, v28, v29
	v_cvt_pk_bf16_f32 v25, v30, v31
	v_add_f32_e32 v36, v37, v36
	v_mul_f32_e32 v37, v79, v79
	v_mul_f32_e32 v47, v77, v77
	v_pk_add_f32 v[56:57], v[26:27], v[62:63]
	v_cvt_pk_bf16_f32 v26, v58, v59
	v_fmac_f32_e32 v37, v78, v78
	v_cvt_pk_bf16_f32 v27, v56, v57
	global_store_dwordx4 v[50:51], v[24:27], off
	v_fmac_f32_e32 v47, v76, v76
	v_add_f32_e32 v37, v37, v47
	v_mul_f32_e32 v24, v29, v29
	v_mul_f32_e32 v25, v31, v31
	v_fmac_f32_e32 v24, v28, v28
	v_fmac_f32_e32 v25, v30, v30
	v_add_f32_e32 v24, v24, v25
	v_mul_f32_e32 v25, v59, v59
	v_mul_f32_e32 v26, v57, v57
	v_add_f32_e32 v39, v39, v40
	v_mul_f32_e32 v40, v83, v83
	s_waitcnt vmcnt(6)
	v_lshlrev_b32_e32 v68, 16, v88
	v_and_b32_e32 v69, 0xffff0000, v88
	v_add_f32_e32 v36, v36, v37
	v_fmac_f32_e32 v25, v58, v58
	v_fmac_f32_e32 v26, v56, v56
	v_fmac_f32_e32 v40, v82, v82
	v_lshlrev_b32_e32 v70, 16, v89
	v_and_b32_e32 v71, 0xffff0000, v89
	v_lshlrev_b32_e32 v82, 16, v90
	v_add_f32_e32 v36, v46, v36
	v_and_b32_e32 v83, 0xffff0000, v90
	v_lshlrev_b32_e32 v46, 16, v91
	v_and_b32_e32 v47, 0xffff0000, v91
	v_add_f32_e32 v25, v25, v26
	v_pk_add_f32 v[20:21], v[20:21], v[68:69]
	v_add_f32_e32 v26, v24, v25
	v_pk_add_f32 v[22:23], v[22:23], v[70:71]
	v_pk_add_f32 v[24:25], v[18:19], v[46:47]
	v_pk_add_f32 v[18:19], v[16:17], v[82:83]
	v_mul_f32_e32 v17, v21, v21
	v_cvt_pk_bf16_f32 v16, v20, v21
	v_fmac_f32_e32 v17, v20, v20
	v_mul_f32_e32 v20, v23, v23
	v_fmac_f32_e32 v20, v22, v22
	v_add_f32_e32 v17, v17, v20
	v_mul_f32_e32 v20, v19, v19
	v_mul_f32_e32 v21, v25, v25
	v_fmac_f32_e32 v20, v18, v18
	v_fmac_f32_e32 v21, v24, v24
	v_add_f32_e32 v20, v20, v21
	v_add_f32_e32 v17, v17, v20
	v_add_f32_e32 v20, v26, v17
	ds_bpermute_b32 v21, v180, v20
	s_waitcnt vmcnt(3)
; __device__ __forceinline__ unsigned cvt_pk_bf16(float lo, float hi) { unsigned r; asm volatile("v_cvt_pk_bf16_f32 %0, %1, %2" : "=v"(r) : "v"(lo), "v"(hi)); return r; }
; template <bool RD32>
; __device__ __forceinline__ void res_rows(const float* __restrict__ xold32, const bf16_t* __restrict__ xoldb, bf16_t* __restrict__ xb, float* __restrict__ ssq, const f32x4 (&acc)[2][2][4][2], int row0, int col0, int slot) {
;     ...
;     for (int idx = 0; idx < 8; ++idx) {
;         const int ai = idx >> 2, m = idx & 3; const int r = row0 + ai * HALF + m * 16; const size_t off = (size_t)r * D + col0;
;         if (idx < 7) { const int ai2 = (idx + 1) >> 2, m2 = (idx + 1) & 3; const size_t off2 = (size_t)(row0 + ai2 * HALF + m2 * 16) * D + col0;
; #pragma unroll
;             for (int bj = 0; bj < 2; ++bj) ld(off2 + bj * HALF, xo[(idx + 1) & 1][bj][0], xo[(idx + 1) & 1][bj][1]); }
;         float ss = 0.f;
; #pragma unroll
;         for (int bj = 0; bj < 2; ++bj) { const f32x4 x0 = xo[idx & 1][bj][0] + acc[ai][bj][m][0], x1 = xo[idx & 1][bj][1] + acc[ai][bj][m][1];
;             u32x4 w; w.x = cvt_pk_bf16(x0[0], x0[1]); w.y = cvt_pk_bf16(x0[2], x0[3]); w.z = cvt_pk_bf16(x1[0], x1[1]); w.w = cvt_pk_bf16(x1[2], x1[3]);
;             *(u32x4*)(xb + off + bj * HALF) = w;
;             ss += ((x0[0] * x0[0] + x0[1] * x0[1]) + (x0[2] * x0[2] + x0[3] * x0[3])) + ((x1[0] * x1[0] + x1[1] * x1[1]) + (x1[2] * x1[2] + x1[3] * x1[3])); }
;         ss += __shfl_xor(ss, 16); ss += __shfl_xor(ss, 32);
;         ssv[idx] = ss;
;     }
;     const int fq = slot >> 6;
; #pragma unroll
;     for (int j = 0; j < 2; ++j) { const float v = fq == 0 ? ssv[j] : fq == 1 ? ssv[2 + j] : fq == 2 ? ssv[4 + j] : ssv[6 + j]; const int idx = 2 * fq + j;
;         ssq[(size_t)(row0 + (idx >> 2) * HALF + (idx & 3) * 16) * 16 + (slot & 15)] = v; }
	v_lshlrev_b32_e32 v42, 16, v52
	v_and_b32_e32 v43, 0xffff0000, v52
	v_lshlrev_b32_e32 v44, 16, v53
	v_and_b32_e32 v45, 0xffff0000, v53
	v_lshlrev_b32_e32 v52, 16, v54
	v_and_b32_e32 v53, 0xffff0000, v54
	v_lshlrev_b32_e32 v54, 16, v55
	v_and_b32_e32 v55, 0xffff0000, v55
	v_cvt_pk_bf16_f32 v17, v22, v23
	v_cvt_pk_bf16_f32 v18, v18, v19
	v_cvt_pk_bf16_f32 v19, v24, v25
	global_store_dwordx4 v[48:49], v[16:19], off offset:256
	v_pk_add_f32 v[14:15], v[14:15], v[44:45]
	v_pk_add_f32 v[12:13], v[12:13], v[42:43]
	s_waitcnt lgkmcnt(0)
	v_add_f32_e32 v16, v20, v21
	v_pk_add_f32 v[20:21], v[8:9], v[52:53]
	v_cvt_pk_bf16_f32 v8, v12, v13
	v_cvt_pk_bf16_f32 v9, v14, v15
	v_pk_add_f32 v[18:19], v[10:11], v[54:55]
	v_cvt_pk_bf16_f32 v10, v20, v21
	s_waitcnt vmcnt(3)
	v_lshlrev_b32_e32 v64, 16, v72
	v_cvt_pk_bf16_f32 v11, v18, v19
	global_store_dwordx4 v[104:105], v[8:11], off
	v_and_b32_e32 v65, 0xffff0000, v72
	v_lshlrev_b32_e32 v66, 16, v73
	v_mul_f32_e32 v8, v13, v13
	v_mul_f32_e32 v9, v15, v15
	v_fmac_f32_e32 v8, v12, v12
	v_fmac_f32_e32 v9, v14, v14
	v_add_f32_e32 v8, v8, v9
	v_mul_f32_e32 v9, v21, v21
	v_mul_f32_e32 v10, v19, v19
	v_fmac_f32_e32 v9, v20, v20
	v_fmac_f32_e32 v10, v18, v18
	v_and_b32_e32 v67, 0xffff0000, v73
	v_lshlrev_b32_e32 v72, 16, v74
	v_and_b32_e32 v73, 0xffff0000, v74
	v_lshlrev_b32_e32 v74, 16, v75
	v_and_b32_e32 v75, 0xffff0000, v75
	v_add_f32_e32 v9, v9, v10
	v_pk_add_f32 v[4:5], v[4:5], v[64:65]
	v_add_f32_e32 v10, v8, v9
	v_pk_add_f32 v[6:7], v[6:7], v[66:67]
	v_pk_add_f32 v[8:9], v[2:3], v[74:75]
	v_pk_add_f32 v[2:3], v[0:1], v[72:73]
	v_mul_f32_e32 v1, v5, v5
	v_add_f32_e32 v38, v38, v39
	v_mul_f32_e32 v39, v93, v93
	v_cvt_pk_bf16_f32 v0, v4, v5
	v_fmac_f32_e32 v1, v4, v4
	v_mul_f32_e32 v4, v7, v7
	v_fmac_f32_e32 v39, v92, v92
	v_fmac_f32_e32 v4, v6, v6
	v_add_f32_e32 v39, v39, v40
	v_mul_f32_e32 v40, v99, v99
	v_mul_f32_e32 v41, v95, v95
	v_add_f32_e32 v1, v1, v4
	v_mul_f32_e32 v4, v3, v3
	v_mul_f32_e32 v5, v9, v9
	v_fmac_f32_e32 v40, v98, v98
	v_fmac_f32_e32 v41, v94, v94
	v_fmac_f32_e32 v4, v2, v2
	v_fmac_f32_e32 v5, v8, v8
	v_add_f32_e32 v40, v40, v41
	v_add_f32_e32 v4, v4, v5
	v_add_f32_e32 v39, v39, v40
	v_add_f32_e32 v1, v1, v4
	v_add_f32_e32 v40, v38, v39
	v_add_f32_e32 v4, v10, v1
	ds_bpermute_b32 v35, v180, v34
	ds_bpermute_b32 v41, v180, v40
	ds_bpermute_b32 v37, v180, v36
	ds_bpermute_b32 v5, v180, v4
	v_cvt_pk_bf16_f32 v1, v6, v7
	v_cvt_pk_bf16_f32 v2, v2, v3
	v_lshlrev_b32_e32 v87, 2, v85
	v_add_f32_e32 v84, v84, v86
	v_add_f32_e32 v38, v97, v120
	s_waitcnt lgkmcnt(3)
	v_add_f32_e32 v34, v34, v35
	s_waitcnt lgkmcnt(2)
	v_add_f32_e32 v40, v40, v41
	s_waitcnt lgkmcnt(1)
	v_add_f32_e32 v36, v36, v37
	v_cvt_pk_bf16_f32 v3, v8, v9
	global_store_dwordx4 v[32:33], v[0:3], off offset:256
	ds_bpermute_b32 v85, v87, v96
	ds_bpermute_b32 v86, v87, v84
	s_waitcnt lgkmcnt(2)
	v_add_f32_e32 v2, v4, v5
	ds_bpermute_b32 v39, v87, v38
	ds_bpermute_b32 v35, v87, v34
	ds_bpermute_b32 v41, v87, v40
	ds_bpermute_b32 v37, v87, v36
	ds_bpermute_b32 v17, v87, v16
	ds_bpermute_b32 v3, v87, v2
	s_and_b32 s14, s29, 12
	s_or_b32 s14, s14, s11
	s_lshl_b32 s14, s14, 2
	v_bitop3_b32 v0, s29, v216, v177 bitop3:0xc8
	s_add_u32 s46, s18, s14
	v_cmp_lt_u32_e32 vcc, 63, v179
	v_add_u32_e32 v0, v164, v0
	s_addc_u32 s47, s19, 0
	s_and_saveexec_b64 s[14:15], vcc
	s_xor_b64 s[48:49], exec, s[14:15]
	s_cbranch_execz .LBB0_626
	v_ashrrev_i32_e32 v4, 6, v179
	v_cmp_lt_i32_e32 vcc, 1, v4
	s_mov_b64 s[42:43], 0
	s_and_saveexec_b64 s[14:15], vcc
	s_xor_b64 s[50:51], exec, s[14:15]
	s_cbranch_execnz .LBB0_631
	s_or_saveexec_b64 s[50:51], s[50:51]
	v_cmp_ne_u32_e32 vcc, 1, v4
	s_xor_b64 exec, exec, s[50:51]
	s_cbranch_execnz .LBB0_634

; __global__ void __launch_bounds__(512, 2) fwd_megakernel(Params p) {
	.amdhsa_kernel _Z14fwd_megakernel6Params
		.amdhsa_group_segment_fixed_size 0
		.amdhsa_private_segment_fixed_size 0
		.amdhsa_kernarg_size 400
		.amdhsa_user_sgpr_count 2
		.amdhsa_user_sgpr_dispatch_ptr 0
		.amdhsa_user_sgpr_queue_ptr 0
		.amdhsa_user_sgpr_kernarg_segment_ptr 1
		.amdhsa_user_sgpr_dispatch_id 0
		.amdhsa_user_sgpr_kernarg_preload_length 0
		.amdhsa_user_sgpr_kernarg_preload_offset 0
		.amdhsa_user_sgpr_private_segment_size 0
		.amdhsa_uses_dynamic_stack 0
		.amdhsa_enable_private_segment 0
		.amdhsa_system_sgpr_workgroup_id_x 1
		.amdhsa_system_sgpr_workgroup_id_y 0
		.amdhsa_system_sgpr_workgroup_id_z 0
		.amdhsa_system_sgpr_workgroup_info 0
		.amdhsa_system_vgpr_workitem_id 2
		.amdhsa_next_free_vgpr 256
		.amdhsa_next_free_sgpr 100
		.amdhsa_accum_offset 256
		.amdhsa_reserve_vcc 1
		.amdhsa_float_round_mode_32 0
		.amdhsa_float_round_mode_16_64 0
		.amdhsa_float_denorm_mode_32 3
		.amdhsa_float_denorm_mode_16_64 3
		.amdhsa_dx10_clamp 1
		.amdhsa_ieee_mode 1
		.amdhsa_fp16_overflow 0
		.amdhsa_tg_split 0
		.amdhsa_exception_fp_ieee_invalid_op 0
		.amdhsa_exception_fp_denorm_src 0
		.amdhsa_exception_fp_ieee_div_zero 0
		.amdhsa_exception_fp_ieee_overflow 0
		.amdhsa_exception_fp_ieee_underflow 0
		.amdhsa_exception_fp_ieee_inexact 0
		.amdhsa_exception_int_div_zero 0
	.end_amdhsa_kernel

; __global__ void __launch_bounds__(512, 2) fwd_megakernel(Params p) {
amdhsa.kernels:
  - .agpr_count:     0
    .args:
      - .offset:         0
        .size:           144
        .value_kind:     by_value
      - .offset:         144
        .size:           4
        .value_kind:     hidden_block_count_x
      - .offset:         148
        .size:           4
        .value_kind:     hidden_block_count_y
      - .offset:         152
        .size:           4
        .value_kind:     hidden_block_count_z
      - .offset:         156
        .size:           2
        .value_kind:     hidden_group_size_x
      - .offset:         158
        .size:           2
        .value_kind:     hidden_group_size_y
      - .offset:         160
        .size:           2
        .value_kind:     hidden_group_size_z
      - .offset:         162
        .size:           2
        .value_kind:     hidden_remainder_x
      - .offset:         164
        .size:           2
        .value_kind:     hidden_remainder_y
      - .offset:         166
        .size:           2
        .value_kind:     hidden_remainder_z
      - .offset:         184
        .size:           8
        .value_kind:     hidden_global_offset_x
      - .offset:         192
        .size:           8
        .value_kind:     hidden_global_offset_y
      - .offset:         200
        .size:           8
        .value_kind:     hidden_global_offset_z
      - .offset:         208
        .size:           2
        .value_kind:     hidden_grid_dims
      - .offset:         232
        .size:           8
        .value_kind:     hidden_multigrid_sync_arg
      - .offset:         264
        .size:           4
        .value_kind:     hidden_dynamic_lds_size
    .group_segment_fixed_size: 0
    .kernarg_segment_align: 8
    .kernarg_segment_size: 400
    .language:       OpenCL C
    .language_version:
      - 2
      - 0
    .max_flat_workgroup_size: 512
    .name:           _Z14fwd_megakernel6Params
    .private_segment_fixed_size: 0
    .sgpr_count:     106
    .sgpr_spill_count: 188
    .symbol:         _Z14fwd_megakernel6Params.kd
    .uniform_work_group_size: 1
    .uses_dynamic_stack: false
    .vgpr_count:     256
    .vgpr_spill_count: 0
    .wavefront_size: 64
